# attention MODE0 loop: K/V fragment prefetch with counted lgkmcnt waits + waves 4-7 staggered copy
# speedup vs baseline: 1.0039x; 1.0039x over previous
; #define SBAR() __builtin_amdgcn_sched_barrier(0)
; #define QKT(P0, P1, KS) do { if (MODE == 1) qkt_lds(P0, P1, KS, qs, r32, hi); else qkt(P0, P1, KS, qr, r32, hi); } while (0)
; __device__ __forceinline__ void finishSM(f32x16& p0, f32x16& p1, float alpha, float& l_reg, bf16x8& pa0, bf16x8& pa1, bf16x8& pa2, bf16x8& pa3) {
;   for (int r = 0; r < 16; ++r) p1[r] = __builtin_amdgcn_exp2f(p1[r]);
;   float ps = 0; for (int r = 0; r < 16; ++r) ps += p0[r]; for (int r = 0; r < 16; ++r) ps += p1[r];
;   { auto rr = __builtin_amdgcn_permlane32_swap(__float_as_uint(ps), __float_as_uint(ps), false, false);
;     ps = __uint_as_float(rr[0]) + __uint_as_float(rr[1]); }
;   l_reg = l_reg * alpha + ps;
;     ...
;   PK4(p0, 0, pa0); PK4(p0, 8, pa1); PK4(p1, 0, pa2); PK4(p1, 8, pa3);
;     ...
; }
; __device__ __forceinline__ void qkt(f32x16& p0, f32x16& p1, const u16* Ks, const bf16x8* qr, int r32, int hi) {
;   p0 = f32x16{}; p1 = f32x16{};
;   for (int d0 = 0; d0 < 8; ++d0) { int cb = (d0 * 16 + hi * 8) * 2;
;     bf16x8 b0 = *reinterpret_cast<const bf16x8*>((const char*)Ks + KSWZ(r32, cb));
;     bf16x8 b1 = *reinterpret_cast<const bf16x8*>((const char*)Ks + KSWZ(32 + r32, cb));
;     p0 = __builtin_amdgcn_mfma_f32_32x32x16_bf16(b0, qr[d0], p0, 0, 0, 0);
;     p1 = __builtin_amdgcn_mfma_f32_32x32x16_bf16(b1, qr[d0], p1, 0, 0, 0); }
; }
; template <int MODE> ...
;     ...
;     for (int j = 1; j + 1 < NT; j += 2) {
;       const int s0_ = sj, s1_ = sj == 2 ? 0 : sj + 1, s2_ = s1_ == 2 ? 0 : s1_ + 1;
;       SBAR(); QKT(pB0, pB1, (u16*)((char*)K_lds + s0_ * SHM_K));
;       finishSM(pA0, pA1, alA, l_reg, pa0, pa1, pa2, pa3); SBAR();
;       { const int tn = (j + 2 < NT) ? j + 2 : NT - 1; SLOAD(SO, tn); } SBAR();
;       pv_d0(o, vb0 + s2_ * (int)SHM_V, pa0, pa1, pa2, pa3); partialSM(pB0, pB1, m_reg, mnB, alB);
.LBB0_474:
	s_add_i32 s7, s89, 1
	s_cmp_lg_u32 s89, 2
	s_cselect_b32 s66, s7, 0
	s_add_i32 s7, s66, 1
	s_cmp_lg_u32 s66, 2
	s_mov_b32 s6, s89
	s_cselect_b32 s89, s7, 0
	s_lshl_b32 s93, s6, 14
	s_add_i32 s6, s93, 0
	v_add_u32_e32 v254, s6, v189
	ds_read_b128 v[68:71], v254 offset:49152
	ds_read_b128 v[72:75], v254 offset:57344
	v_add_u32_e32 v254, s6, v190
	ds_read_b128 v[220:223], v254 offset:49152
	ds_read_b128 v[224:227], v254 offset:57344
	v_add_u32_e32 v254, s6, v191
	ds_read_b128 v[228:231], v254 offset:49152
	ds_read_b128 v[232:235], v254 offset:57344
	v_add_u32_e32 v254, s6, v192
	ds_read_b128 v[236:239], v254 offset:49152
	ds_read_b128 v[240:243], v254 offset:57344
	v_add_u32_e32 v254, s6, v193
	ds_read_b128 v[246:249], v254 offset:49152
	ds_read_b128 v[250:253], v254 offset:57344
	s_waitcnt lgkmcnt(9)
	v_mfma_f32_32x32x16_bf16 v[84:99], v[68:71], v[100:103], 0
	v_exp_f32_e32 v160, v160
	v_exp_f32_e32 v161, v161
	v_exp_f32_e32 v158, v158
	v_exp_f32_e32 v159, v159
	v_exp_f32_e32 v156, v156
	v_exp_f32_e32 v157, v157
	v_exp_f32_e32 v154, v154
	s_waitcnt lgkmcnt(8)
	v_mfma_f32_32x32x16_bf16 v[68:83], v[72:75], v[100:103], 0
	v_exp_f32_e32 v155, v155
	v_exp_f32_e32 v152, v152
	v_exp_f32_e32 v153, v153
	v_exp_f32_e32 v150, v150
	v_exp_f32_e32 v151, v151
	v_exp_f32_e32 v148, v148
	v_exp_f32_e32 v149, v149
	s_waitcnt lgkmcnt(7)
	v_mfma_f32_32x32x16_bf16 v[84:99], v[220:223], v[104:107], v[84:99]
	s_waitcnt lgkmcnt(6)
	v_mfma_f32_32x32x16_bf16 v[68:83], v[224:227], v[104:107], v[68:83]
	v_add_u32_e32 v254, s6, v194
	ds_read_b128 v[220:223], v254 offset:49152
	ds_read_b128 v[224:227], v254 offset:57344
	s_waitcnt lgkmcnt(7)
	v_mfma_f32_32x32x16_bf16 v[84:99], v[228:231], v[108:111], v[84:99]
	s_waitcnt lgkmcnt(6)
	v_mfma_f32_32x32x16_bf16 v[68:83], v[232:235], v[108:111], v[68:83]
	v_add_u32_e32 v254, s6, v195
	ds_read_b128 v[228:231], v254 offset:49152
	ds_read_b128 v[232:235], v254 offset:57344
	s_waitcnt lgkmcnt(7)
	v_mfma_f32_32x32x16_bf16 v[84:99], v[236:239], v[112:115], v[84:99]
	s_waitcnt lgkmcnt(6)
	v_mfma_f32_32x32x16_bf16 v[68:83], v[240:243], v[112:115], v[68:83]
	v_add_u32_e32 v254, s6, v196
	ds_read_b128 v[236:239], v254 offset:49152
	ds_read_b128 v[240:243], v254 offset:57344
	s_waitcnt lgkmcnt(7)
	v_mfma_f32_32x32x16_bf16 v[84:99], v[246:249], v[116:119], v[84:99]
	s_waitcnt lgkmcnt(6)
	v_mfma_f32_32x32x16_bf16 v[68:83], v[250:253], v[116:119], v[68:83]
	s_waitcnt lgkmcnt(5)
	v_mfma_f32_32x32x16_bf16 v[84:99], v[220:223], v[120:123], v[84:99]
	s_waitcnt lgkmcnt(4)
	v_mfma_f32_32x32x16_bf16 v[68:83], v[224:227], v[120:123], v[68:83]
	s_waitcnt lgkmcnt(3)
	v_mfma_f32_32x32x16_bf16 v[84:99], v[228:231], v[124:127], v[84:99]
	s_waitcnt lgkmcnt(2)
	v_mfma_f32_32x32x16_bf16 v[68:83], v[232:235], v[124:127], v[68:83]
	v_exp_f32_e32 v2, v162
	v_exp_f32_e32 v162, v163
	v_add_f32_e32 v163, 0, v216
	v_add_f32_e32 v163, v218, v163
	v_add_f32_e32 v163, v214, v163
	v_add_f32_e32 v163, v217, v163
	v_add_f32_e32 v163, v213, v163
	v_add_f32_e32 v163, v215, v163
	v_add_f32_e32 v163, v211, v163
	v_add_f32_e32 v163, v212, v163
	v_add_f32_e32 v163, v208, v163
	v_add_f32_e32 v163, v210, v163
	v_add_f32_e32 v163, v207, v163
	v_add_f32_e32 v163, v209, v163
	v_add_f32_e32 v163, v204, v163
	v_add_f32_e32 v163, v206, v163
	v_add_f32_e32 v163, v203, v163
	v_add_f32_e32 v163, v205, v163
	v_add_f32_e32 v163, v2, v163
	v_add_f32_e32 v163, v162, v163
	v_add_f32_e32 v163, v160, v163
	v_add_f32_e32 v163, v161, v163
	v_add_f32_e32 v163, v158, v163
	v_add_f32_e32 v163, v159, v163
	v_add_f32_e32 v163, v156, v163
	v_add_f32_e32 v163, v157, v163
	v_add_f32_e32 v163, v154, v163
	v_add_f32_e32 v163, v155, v163
	s_waitcnt lgkmcnt(1)
	v_mfma_f32_32x32x16_bf16 v[84:99], v[236:239], v[128:131], v[84:99]
	v_add_f32_e32 v163, v152, v163
	v_add_f32_e32 v163, v153, v163
	v_add_f32_e32 v163, v150, v163
	v_add_f32_e32 v163, v151, v163
	v_add_f32_e32 v163, v148, v163
	v_add_f32_e32 v200, v149, v163
	v_mov_b32_e32 v201, v200
	s_waitcnt lgkmcnt(0)
	v_mfma_f32_32x32x16_bf16 v[68:83], v[240:243], v[128:131], v[68:83]
	s_lshl_b32 s94, s89, 14
	v_add_u32_e32 v254, s94, v197
	ds_read_b64_tr_b16 v[220:221], v254 offset:0
	ds_read_b64_tr_b16 v[222:223], v254 offset:2048
	ds_read_b64_tr_b16 v[224:225], v254 offset:4096
	ds_read_b64_tr_b16 v[226:227], v254 offset:6144
	ds_read_b64_tr_b16 v[228:229], v254 offset:8192
	ds_read_b64_tr_b16 v[230:231], v254 offset:10240
	ds_read_b64_tr_b16 v[232:233], v254 offset:12288
	ds_read_b64_tr_b16 v[234:235], v254 offset:14336
	ds_read_b64_tr_b16 v[236:237], v254 offset:512
	ds_read_b64_tr_b16 v[238:239], v254 offset:2560
	v_cvt_pk_bf16_f32 v216, v216, v218
	v_cvt_pk_bf16_f32 v217, v214, v217
	v_cvt_pk_bf16_f32 v218, v213, v215
	v_cvt_pk_bf16_f32 v219, v211, v212
	v_cvt_pk_bf16_f32 v208, v208, v210
	v_cvt_pk_bf16_f32 v209, v207, v209
	v_cvt_pk_bf16_f32 v210, v204, v206
	v_cvt_pk_bf16_f32 v211, v203, v205
	v_cvt_pk_bf16_f32 v202, v2, v162
	v_cvt_pk_bf16_f32 v203, v160, v161
	v_cvt_pk_bf16_f32 v204, v158, v159
	v_permlane32_swap_b32_e32 v200, v201
	v_cvt_pk_bf16_f32 v205, v156, v157
	v_permlane32_swap_b32_e32 v202, v204
	v_cvt_pk_bf16_f32 v212, v154, v155
	v_cvt_pk_bf16_f32 v213, v152, v153
	v_cvt_pk_bf16_f32 v214, v150, v151
	v_cvt_pk_bf16_f32 v215, v148, v149
	v_permlane32_swap_b32_e32 v216, v218
	v_permlane32_swap_b32_e32 v217, v219
	v_permlane32_swap_b32_e32 v208, v210
	v_permlane32_swap_b32_e32 v209, v211
	v_permlane32_swap_b32_e32 v203, v205
	v_permlane32_swap_b32_e32 v212, v214
	v_permlane32_swap_b32_e32 v213, v215
	s_add_i32 s91, s16, -1
	s_min_u32 s6, s91, s90
	s_add_i32 s6, s6, s88
	s_lshl_b32 s6, s6, 6
	v_add_u32_e32 v148, s6, v167
	v_add_u32_e32 v150, s6, v185
	v_ashrrev_i32_e32 v149, 31, v148
	v_ashrrev_i32_e32 v151, 31, v150
	v_lshlrev_b64 v[156:157], 8, v[148:149]
	v_lshlrev_b64 v[158:159], 8, v[150:151]
	v_or_b32_e32 v156, v156, v182
	v_or_b32_e32 v158, v158, v182
	v_lshl_add_u64 v[148:149], s[58:59], 0, v[156:157]
	v_lshl_add_u64 v[150:151], s[58:59], 0, v[158:159]
	v_lshl_add_u64 v[156:157], s[64:65], 0, v[156:157]
	v_lshl_add_u64 v[158:159], s[64:65], 0, v[158:159]
	global_load_dwordx4 v[152:155], v[148:149], off
	s_nop 0
	global_load_dwordx4 v[148:151], v[150:151], off
	s_nop 0
	global_load_dwordx4 v[160:163], v[156:157], off
	s_nop 0
	global_load_dwordx4 v[156:159], v[158:159], off
	s_waitcnt lgkmcnt(8)
; #define SBAR() __builtin_amdgcn_sched_barrier(0)
; __device__ __forceinline__ void partialSM(f32x16& p0, f32x16& p1, float& m_reg, float& mn, float& alpha) {
;   constexpr float C = SCALE * 1.4426950408889634f;
;   float pmax = p0[0]; for (int r = 1; r < 16; ++r) pmax = fmaxf(pmax, p0[r]); for (int r = 0; r < 16; ++r) pmax = fmaxf(pmax, p1[r]);
;   { auto rr = __builtin_amdgcn_permlane32_swap(__float_as_uint(pmax), __float_as_uint(pmax), false, false);
;     pmax = fmaxf(__uint_as_float(rr[0]), __uint_as_float(rr[1])); }
;   if (__builtin_expect(__all(pmax - m_reg <= THR / SCALE), 1)) { mn = m_reg; alpha = 1.f; }
;   else { mn = fmaxf(m_reg, pmax); alpha = __builtin_amdgcn_exp2f((m_reg - mn) * C); m_reg = mn; }
; template <int D0> __device__ __forceinline__ void pv_one(f32x16& od, int vb, bf16x8 pa0, bf16x8 pa1, bf16x8 pa2, bf16x8 pa3) {
;   const s16x4 l0 = tr_read<v_rd_off(D0, 0, 0)>(vb), h0 = tr_read<v_rd_off(D0, 0, 1)>(vb), l1 = tr_read<v_rd_off(D0, 1, 0)>(vb), h1 = tr_read<v_rd_off(D0, 1, 1)>(vb);
;   const s16x4 l2 = tr_read<v_rd_off(D0, 2, 0)>(vb), h2 = tr_read<v_rd_off(D0, 2, 1)>(vb), l3 = tr_read<v_rd_off(D0, 3, 0)>(vb), h3 = tr_read<v_rd_off(D0, 3, 1)>(vb);
;   asm volatile("s_waitcnt lgkmcnt(0)" ::: "memory"); SBAR();
;     ...
;   od = __builtin_amdgcn_mfma_f32_32x32x16_bf16(pa0, PK(l0, h0), od, 0, 0, 0);
;   od = __builtin_amdgcn_mfma_f32_32x32x16_bf16(pa1, PK(l1, h1), od, 0, 0, 0);
;   od = __builtin_amdgcn_mfma_f32_32x32x16_bf16(pa2, PK(l2, h2), od, 0, 0, 0);
;   od = __builtin_amdgcn_mfma_f32_32x32x16_bf16(pa3, PK(l3, h3), od, 0, 0, 0);
;     ...
; }
; __device__ __forceinline__ void pv_d0(f32x16* o, int vb, bf16x8 pa0, bf16x8 pa1, bf16x8 pa2, bf16x8 pa3) {
;   pv_one<0>(o[0], vb, pa0, pa1, pa2, pa3); pv_one<1>(o[1], vb, pa0, pa1, pa2, pa3); pv_one<2>(o[2], vb, pa0, pa1, pa2, pa3); pv_one<3>(o[3], vb, pa0, pa1, pa2, pa3);
	v_mfma_f32_32x32x16_bf16 v[52:67], v[216:219], v[220:223], v[52:67]
	ds_read_b64_tr_b16 v[240:241], v254 offset:4608
	ds_read_b64_tr_b16 v[242:243], v254 offset:6656
	s_waitcnt lgkmcnt(8)
	v_mfma_f32_32x32x16_bf16 v[52:67], v[208:211], v[224:227], v[52:67]
	ds_read_b64_tr_b16 v[220:221], v254 offset:8704
	ds_read_b64_tr_b16 v[222:223], v254 offset:10752
	s_waitcnt lgkmcnt(8)
	v_mfma_f32_32x32x16_bf16 v[52:67], v[202:205], v[228:231], v[52:67]
	ds_read_b64_tr_b16 v[224:225], v254 offset:12800
	ds_read_b64_tr_b16 v[226:227], v254 offset:14848
	s_waitcnt lgkmcnt(8)
	v_mfma_f32_32x32x16_bf16 v[52:67], v[212:215], v[232:235], v[52:67]
	ds_read_b64_tr_b16 v[228:229], v254 offset:1024
	ds_read_b64_tr_b16 v[230:231], v254 offset:3072
	s_waitcnt lgkmcnt(8)
	v_mfma_f32_32x32x16_bf16 v[36:51], v[216:219], v[236:239], v[36:51]
	ds_read_b64_tr_b16 v[232:233], v254 offset:5120
	ds_read_b64_tr_b16 v[234:235], v254 offset:7168
	s_waitcnt lgkmcnt(8)
	v_mfma_f32_32x32x16_bf16 v[36:51], v[208:211], v[240:243], v[36:51]
	ds_read_b64_tr_b16 v[236:237], v254 offset:9216
	ds_read_b64_tr_b16 v[238:239], v254 offset:11264
	s_waitcnt lgkmcnt(8)
	v_mfma_f32_32x32x16_bf16 v[36:51], v[202:205], v[220:223], v[36:51]
	ds_read_b64_tr_b16 v[240:241], v254 offset:13312
	ds_read_b64_tr_b16 v[242:243], v254 offset:15360
	s_waitcnt lgkmcnt(8)
	v_mfma_f32_32x32x16_bf16 v[36:51], v[212:215], v[224:227], v[36:51]
	ds_read_b64_tr_b16 v[220:221], v254 offset:1536
	ds_read_b64_tr_b16 v[222:223], v254 offset:3584
	s_waitcnt lgkmcnt(8)
	v_mfma_f32_32x32x16_bf16 v[20:35], v[216:219], v[228:231], v[20:35]
	ds_read_b64_tr_b16 v[224:225], v254 offset:5632
	ds_read_b64_tr_b16 v[226:227], v254 offset:7680
	s_waitcnt lgkmcnt(8)
	v_mfma_f32_32x32x16_bf16 v[20:35], v[208:211], v[232:235], v[20:35]
	ds_read_b64_tr_b16 v[228:229], v254 offset:9728
	ds_read_b64_tr_b16 v[230:231], v254 offset:11776
	s_waitcnt lgkmcnt(8)
	v_mfma_f32_32x32x16_bf16 v[20:35], v[202:205], v[236:239], v[20:35]
	ds_read_b64_tr_b16 v[232:233], v254 offset:13824
	ds_read_b64_tr_b16 v[234:235], v254 offset:15872
	s_waitcnt lgkmcnt(8)
	v_mfma_f32_32x32x16_bf16 v[20:35], v[212:215], v[240:243], v[20:35]
	s_waitcnt lgkmcnt(6)
	v_mfma_f32_32x32x16_bf16 v[4:19], v[216:219], v[220:223], v[4:19]
	v_max_f32_e32 v2, v85, v85
	s_waitcnt vmcnt(4)
	s_waitcnt lgkmcnt(4)
	v_mfma_f32_32x32x16_bf16 v[4:19], v[208:211], v[224:227], v[4:19]
	s_waitcnt lgkmcnt(2)
	v_mfma_f32_32x32x16_bf16 v[4:19], v[202:205], v[228:231], v[4:19]
	v_max_f32_e32 v202, v84, v84
	v_max_f32_e32 v2, v202, v2
	v_max3_f32 v2, v2, v86, v87
	v_max3_f32 v2, v2, v88, v89
	v_max3_f32 v2, v2, v90, v91
	v_max3_f32 v2, v2, v92, v93
	v_max3_f32 v2, v2, v94, v95
	v_max3_f32 v2, v2, v96, v97
	v_max3_f32 v2, v2, v98, v99
	v_max3_f32 v2, v2, v68, v69
	v_max3_f32 v2, v2, v70, v71
	v_max3_f32 v2, v2, v72, v73
	v_max3_f32 v2, v2, v74, v75
	v_max3_f32 v2, v2, v76, v77
	v_max3_f32 v2, v2, v78, v79
	v_max3_f32 v2, v2, v80, v81
	v_max3_f32 v2, v2, v82, v83
	v_mov_b32_e32 v202, v2
	s_nop 1
	v_permlane32_swap_b32_e32 v2, v202
	v_max_f32_e32 v202, v202, v202
	v_max_f32_e32 v2, v2, v2
	v_max_f32_e32 v2, v2, v202
	v_sub_f32_e32 v202, v2, v166
	v_cmp_ge_f32_e32 vcc, s74, v202
	v_max_f32_e32 v202, v166, v166
	v_max_f32_e32 v2, v202, v2
	s_waitcnt lgkmcnt(0)
	v_mfma_f32_32x32x16_bf16 v[4:19], v[212:215], v[232:235], v[4:19]
	v_sub_f32_e32 v202, v166, v2
	s_cmp_eq_u64 vcc, exec
	v_mul_f32_e32 v202, 0x3e0293ee, v202
	s_cselect_b64 s[6:7], -1, 0
	v_exp_f32_e32 v202, v202
	s_lshl_b32 s92, s66, 14
	s_add_i32 s95, s92, 0
	v_add_u32_e32 v203, s95, v184
	s_waitcnt vmcnt(7)
	ds_write_b128 v203, v[136:139]
	v_add_u32_e32 v136, s95, v186
	v_cndmask_b32_e64 v202, v202, 1.0, s[6:7]
	s_waitcnt vmcnt(6)
	ds_write_b128 v136, v[132:135]
	v_add_u32_e32 v132, s95, v187
	s_waitcnt vmcnt(5)
	ds_write_b128 v132, v[144:147] offset:49152
	v_add_u32_e32 v132, s95, v188
	v_cmp_gt_f32_e32 vcc, 1.0, v202
	s_waitcnt vmcnt(4)
	ds_write_b128 v132, v[140:143] offset:49152
	s_cbranch_vccz .LBB0_478
	s_and_saveexec_b64 s[66:67], s[4:5]
	ds_write_b32 v183, v202 offset:128
	s_or_b64 exec, exec, s[66:67]
	s_waitcnt lgkmcnt(0)
	v_add_u32_e32 v144, v181, v180
	ds_read_b128 v[132:135], v144 offset:224
	ds_read_b128 v[136:139], v144 offset:192
	ds_read_b128 v[140:143], v144 offset:160
	ds_read_b128 v[144:147], v144 offset:128
	s_waitcnt lgkmcnt(3)
	v_pk_mul_f32 v[64:65], v[64:65], v[132:133]
	s_waitcnt lgkmcnt(2)
	v_pk_mul_f32 v[60:61], v[60:61], v[136:137]
	s_waitcnt lgkmcnt(1)
	v_pk_mul_f32 v[56:57], v[56:57], v[140:141]
	v_pk_mul_f32 v[66:67], v[66:67], v[134:135]
	v_pk_mul_f32 v[62:63], v[62:63], v[138:139]
	v_pk_mul_f32 v[58:59], v[58:59], v[142:143]
	s_waitcnt lgkmcnt(0)
	v_pk_mul_f32 v[54:55], v[54:55], v[146:147]
	v_pk_mul_f32 v[52:53], v[52:53], v[144:145]
	v_pk_mul_f32 v[48:49], v[48:49], v[132:133]
	v_pk_mul_f32 v[44:45], v[44:45], v[136:137]
	v_pk_mul_f32 v[40:41], v[40:41], v[140:141]
	v_pk_mul_f32 v[50:51], v[50:51], v[134:135]
	v_pk_mul_f32 v[46:47], v[46:47], v[138:139]
	v_pk_mul_f32 v[42:43], v[42:43], v[142:143]
	v_pk_mul_f32 v[38:39], v[38:39], v[146:147]
	v_pk_mul_f32 v[36:37], v[36:37], v[144:145]
	v_pk_mul_f32 v[32:33], v[32:33], v[132:133]
	v_pk_mul_f32 v[28:29], v[28:29], v[136:137]
	v_pk_mul_f32 v[24:25], v[24:25], v[140:141]
	v_pk_mul_f32 v[34:35], v[34:35], v[134:135]
	v_pk_mul_f32 v[30:31], v[30:31], v[138:139]
	v_pk_mul_f32 v[26:27], v[26:27], v[142:143]
	v_pk_mul_f32 v[22:23], v[22:23], v[146:147]
	v_pk_mul_f32 v[20:21], v[20:21], v[144:145]
	v_pk_mul_f32 v[16:17], v[16:17], v[132:133]
	v_pk_mul_f32 v[12:13], v[12:13], v[136:137]
	v_pk_mul_f32 v[8:9], v[8:9], v[140:141]
	v_pk_mul_f32 v[18:19], v[18:19], v[134:135]
	v_pk_mul_f32 v[14:15], v[14:15], v[138:139]
	v_pk_mul_f32 v[10:11], v[10:11], v[142:143]
	v_pk_mul_f32 v[6:7], v[6:7], v[146:147]
	v_pk_mul_f32 v[4:5], v[4:5], v[144:145]
; __device__ __forceinline__ void partialSM(f32x16& p0, f32x16& p1, float& m_reg, float& mn, float& alpha) {
;   constexpr float C = SCALE * 1.4426950408889634f;
;   float pmax = p0[0]; for (int r = 1; r < 16; ++r) pmax = fmaxf(pmax, p0[r]); for (int r = 0; r < 16; ++r) pmax = fmaxf(pmax, p1[r]);
;   { auto rr = __builtin_amdgcn_permlane32_swap(__float_as_uint(pmax), __float_as_uint(pmax), false, false);
;     pmax = fmaxf(__uint_as_float(rr[0]), __uint_as_float(rr[1])); }
;   if (__builtin_expect(__all(pmax - m_reg <= THR / SCALE), 1)) { mn = m_reg; alpha = 1.f; }
;   else { mn = fmaxf(m_reg, pmax); alpha = __builtin_amdgcn_exp2f((m_reg - mn) * C); m_reg = mn; }
;   float mnC = -mn * C;
;   for (int r = 0; r < 16; ++r) p0[r] = fmaf(p0[r], C, mnC); for (int r = 0; r < 16; ++r) p1[r] = fmaf(p1[r], C, mnC);
;   for (int r = 0; r < 16; ++r) p0[r] = __builtin_amdgcn_exp2f(p0[r]);
; }
; __device__ __forceinline__ void qkt(f32x16& p0, f32x16& p1, const u16* Ks, const bf16x8* qr, int r32, int hi) {
;   p0 = f32x16{}; p1 = f32x16{};
;   for (int d0 = 0; d0 < 8; ++d0) { int cb = (d0 * 16 + hi * 8) * 2;
;     bf16x8 b0 = *reinterpret_cast<const bf16x8*>((const char*)Ks + KSWZ(r32, cb));
;     bf16x8 b1 = *reinterpret_cast<const bf16x8*>((const char*)Ks + KSWZ(32 + r32, cb));
;     p0 = __builtin_amdgcn_mfma_f32_32x32x16_bf16(b0, qr[d0], p0, 0, 0, 0);
;     p1 = __builtin_amdgcn_mfma_f32_32x32x16_bf16(b1, qr[d0], p1, 0, 0, 0); }
; }
.LBB0_478:
	v_cndmask_b32_e64 v2, v2, v166, s[6:7]
	v_mul_f32_e32 v140, 0xbe0293ee, v2
	v_fmamk_f32 v93, v93, 0x3e0293ee, v140
	v_exp_f32_e32 v221, v93
	v_fmamk_f32 v84, v84, 0x3e0293ee, v140
	v_fmamk_f32 v85, v85, 0x3e0293ee, v140
	v_fmamk_f32 v86, v86, 0x3e0293ee, v140
	v_fmamk_f32 v87, v87, 0x3e0293ee, v140
	v_fmamk_f32 v88, v88, 0x3e0293ee, v140
	v_fmamk_f32 v89, v89, 0x3e0293ee, v140
	v_fmamk_f32 v90, v90, 0x3e0293ee, v140
	v_fmamk_f32 v91, v91, 0x3e0293ee, v140
	v_fmamk_f32 v92, v92, 0x3e0293ee, v140
	v_fmamk_f32 v94, v94, 0x3e0293ee, v140
	v_fmamk_f32 v95, v95, 0x3e0293ee, v140
	v_fmamk_f32 v96, v96, 0x3e0293ee, v140
	v_fmamk_f32 v97, v97, 0x3e0293ee, v140
	v_fmamk_f32 v98, v98, 0x3e0293ee, v140
	v_fmamk_f32 v99, v99, 0x3e0293ee, v140
	v_fmamk_f32 v141, v68, 0x3e0293ee, v140
	v_fmamk_f32 v142, v69, 0x3e0293ee, v140
	v_fmamk_f32 v143, v70, 0x3e0293ee, v140
	v_fmamk_f32 v144, v71, 0x3e0293ee, v140
	v_fmamk_f32 v145, v72, 0x3e0293ee, v140
	v_fmamk_f32 v146, v73, 0x3e0293ee, v140
	v_fmamk_f32 v147, v74, 0x3e0293ee, v140
	v_fmamk_f32 v166, v75, 0x3e0293ee, v140
	v_fmamk_f32 v203, v76, 0x3e0293ee, v140
	v_fmamk_f32 v204, v77, 0x3e0293ee, v140
	v_fmamk_f32 v205, v78, 0x3e0293ee, v140
	v_fmamk_f32 v206, v79, 0x3e0293ee, v140
	v_fmamk_f32 v207, v80, 0x3e0293ee, v140
	v_fmamk_f32 v208, v81, 0x3e0293ee, v140
	v_fmamk_f32 v209, v82, 0x3e0293ee, v140
	v_fmac_f32_e32 v140, 0x3e0293ee, v83
	v_exp_f32_e32 v210, v84
	v_exp_f32_e32 v211, v85
	v_exp_f32_e32 v212, v86
	v_exp_f32_e32 v213, v87
	v_exp_f32_e32 v214, v88
	v_exp_f32_e32 v215, v89
	v_exp_f32_e32 v216, v90
	v_exp_f32_e32 v217, v91
	v_exp_f32_e32 v218, v92
	v_exp_f32_e32 v222, v94
	v_exp_f32_e32 v223, v95
	v_exp_f32_e32 v224, v96
	v_exp_f32_e32 v225, v97
	v_exp_f32_e32 v226, v98
	v_exp_f32_e32 v227, v99
	s_waitcnt lgkmcnt(0)
	s_barrier
	v_add_u32_e32 v254, s95, v189
	ds_read_b128 v[68:71], v254 offset:49152
	ds_read_b128 v[72:75], v254 offset:57344
	v_add_u32_e32 v254, s95, v190
	ds_read_b128 v[132:135], v254 offset:49152
	ds_read_b128 v[136:139], v254 offset:57344
	v_add_u32_e32 v254, s95, v191
	ds_read_b128 v[228:231], v254 offset:49152
	ds_read_b128 v[232:235], v254 offset:57344
	v_add_u32_e32 v254, s95, v192
	ds_read_b128 v[236:239], v254 offset:49152
	ds_read_b128 v[240:243], v254 offset:57344
	v_add_u32_e32 v254, s95, v193
	ds_read_b128 v[246:249], v254 offset:49152
	ds_read_b128 v[250:253], v254 offset:57344
	s_waitcnt lgkmcnt(9)
	v_mfma_f32_32x32x16_bf16 v[84:99], v[68:71], v[100:103], 0
	v_exp_f32_e32 v140, v140
	s_waitcnt lgkmcnt(8)
	v_mfma_f32_32x32x16_bf16 v[68:83], v[72:75], v[100:103], 0
	s_waitcnt lgkmcnt(7)
	v_mfma_f32_32x32x16_bf16 v[84:99], v[132:135], v[104:107], v[84:99]
	s_waitcnt lgkmcnt(6)
	v_mfma_f32_32x32x16_bf16 v[68:83], v[136:139], v[104:107], v[68:83]
	v_add_u32_e32 v254, s95, v194
	ds_read_b128 v[132:135], v254 offset:49152
	ds_read_b128 v[136:139], v254 offset:57344
	s_waitcnt lgkmcnt(7)
	v_mfma_f32_32x32x16_bf16 v[84:99], v[228:231], v[108:111], v[84:99]
	s_waitcnt lgkmcnt(6)
	v_mfma_f32_32x32x16_bf16 v[68:83], v[232:235], v[108:111], v[68:83]
	v_add_u32_e32 v254, s95, v195
	ds_read_b128 v[228:231], v254 offset:49152
	ds_read_b128 v[232:235], v254 offset:57344
	s_waitcnt lgkmcnt(7)
	v_mfma_f32_32x32x16_bf16 v[84:99], v[236:239], v[112:115], v[84:99]
	s_waitcnt lgkmcnt(6)
	v_mfma_f32_32x32x16_bf16 v[68:83], v[240:243], v[112:115], v[68:83]
	v_add_u32_e32 v254, s95, v196
	ds_read_b128 v[236:239], v254 offset:49152
	ds_read_b128 v[240:243], v254 offset:57344
	s_waitcnt lgkmcnt(7)
	v_mfma_f32_32x32x16_bf16 v[84:99], v[246:249], v[116:119], v[84:99]
	s_waitcnt lgkmcnt(6)
	v_mfma_f32_32x32x16_bf16 v[68:83], v[250:253], v[116:119], v[68:83]
	s_waitcnt lgkmcnt(5)
	v_mfma_f32_32x32x16_bf16 v[84:99], v[132:135], v[120:123], v[84:99]
	s_waitcnt lgkmcnt(4)
	v_mfma_f32_32x32x16_bf16 v[68:83], v[136:139], v[120:123], v[68:83]
	s_waitcnt lgkmcnt(3)
	v_mfma_f32_32x32x16_bf16 v[84:99], v[228:231], v[124:127], v[84:99]
	s_waitcnt lgkmcnt(2)
	v_mfma_f32_32x32x16_bf16 v[68:83], v[232:235], v[124:127], v[68:83]
	s_waitcnt lgkmcnt(1)
	v_mfma_f32_32x32x16_bf16 v[84:99], v[236:239], v[128:131], v[84:99]
	v_exp_f32_e32 v139, v166
	v_add_f32_e32 v166, 0, v210
	v_add_f32_e32 v166, v211, v166
	v_add_f32_e32 v166, v212, v166
	v_add_f32_e32 v166, v213, v166
	v_add_f32_e32 v166, v214, v166
	v_add_f32_e32 v166, v215, v166
	v_add_f32_e32 v166, v216, v166
	v_add_f32_e32 v166, v217, v166
	v_add_f32_e32 v166, v218, v166
	v_add_f32_e32 v166, v221, v166
	v_add_f32_e32 v166, v222, v166
	v_add_f32_e32 v166, v223, v166
	s_waitcnt lgkmcnt(0)
; #define SBAR() __builtin_amdgcn_sched_barrier(0)
; #define QKT(P0, P1, KS) do { if (MODE == 1) qkt_lds(P0, P1, KS, qs, r32, hi); else qkt(P0, P1, KS, qr, r32, hi); } while (0)
; __device__ __forceinline__ void finishSM(f32x16& p0, f32x16& p1, float alpha, float& l_reg, bf16x8& pa0, bf16x8& pa1, bf16x8& pa2, bf16x8& pa3) {
;   for (int r = 0; r < 16; ++r) p1[r] = __builtin_amdgcn_exp2f(p1[r]);
;   float ps = 0; for (int r = 0; r < 16; ++r) ps += p0[r]; for (int r = 0; r < 16; ++r) ps += p1[r];
;   { auto rr = __builtin_amdgcn_permlane32_swap(__float_as_uint(ps), __float_as_uint(ps), false, false);
;     ps = __uint_as_float(rr[0]) + __uint_as_float(rr[1]); }
;   l_reg = l_reg * alpha + ps;
;     ...
;   PK4(p0, 0, pa0); PK4(p0, 8, pa1); PK4(p1, 0, pa2); PK4(p1, 8, pa3);
;     ...
; }
; template <int MODE> ...
;     ...
;       SBAR(); QKT(pA0, pA1, (u16*)((char*)K_lds + s1_ * SHM_K));
;       finishSM(pB0, pB1, alB, l_reg, pa0, pa1, pa2, pa3); SBAR();
;       { const int tn = (j + 3 < NT) ? j + 3 : NT - 1; SLOAD(SE, tn); } SBAR();
;       pv_d0(o, vb0 + s0_ * (int)SHM_V, pa0, pa1, pa2, pa3); partialSM(pA0, pA1, m_reg, mnA, alA);
	v_mfma_f32_32x32x16_bf16 v[68:83], v[240:243], v[128:131], v[68:83]
	v_add_u32_e32 v254, s93, v197
	ds_read_b64_tr_b16 v[230:231], v254 offset:0
	ds_read_b64_tr_b16 v[232:233], v254 offset:2048
	ds_read_b64_tr_b16 v[234:235], v254 offset:4096
	ds_read_b64_tr_b16 v[236:237], v254 offset:6144
	ds_read_b64_tr_b16 v[238:239], v254 offset:8192
	ds_read_b64_tr_b16 v[240:241], v254 offset:10240
	ds_read_b64_tr_b16 v[242:243], v254 offset:12288
	ds_read_b64_tr_b16 v[244:245], v254 offset:14336
	ds_read_b64_tr_b16 v[246:247], v254 offset:512
	ds_read_b64_tr_b16 v[248:249], v254 offset:2560
	v_exp_f32_e32 v132, v141
	v_add_f32_e32 v166, v224, v166
	v_exp_f32_e32 v133, v142
	v_add_f32_e32 v166, v225, v166
	v_exp_f32_e32 v134, v143
	v_add_f32_e32 v166, v226, v166
	v_exp_f32_e32 v135, v144
	v_add_f32_e32 v166, v227, v166
	v_exp_f32_e32 v136, v145
	v_add_f32_e32 v166, v132, v166
	v_exp_f32_e32 v137, v146
	v_add_f32_e32 v166, v133, v166
	v_exp_f32_e32 v138, v147
	v_add_f32_e32 v166, v134, v166
	v_add_f32_e32 v166, v135, v166
	v_exp_f32_e32 v141, v203
	v_add_f32_e32 v166, v136, v166
	v_exp_f32_e32 v142, v204
	v_add_f32_e32 v166, v137, v166
	v_exp_f32_e32 v143, v205
	v_add_f32_e32 v166, v138, v166
	v_exp_f32_e32 v144, v206
	v_add_f32_e32 v166, v139, v166
	v_exp_f32_e32 v145, v207
	v_add_f32_e32 v166, v141, v166
	v_exp_f32_e32 v146, v208
	v_add_f32_e32 v166, v142, v166
	v_exp_f32_e32 v147, v209
	v_add_f32_e32 v166, v143, v166
	v_add_f32_e32 v166, v144, v166
	v_add_f32_e32 v166, v145, v166
	v_add_f32_e32 v166, v146, v166
	v_add_f32_e32 v166, v147, v166
	v_add_f32_e32 v219, v140, v166
	v_mov_b32_e32 v220, v219
	s_nop 1
	v_permlane32_swap_b32_e32 v219, v220
	v_cvt_pk_bf16_f32 v204, v210, v211
	v_cvt_pk_bf16_f32 v205, v212, v213
	v_cvt_pk_bf16_f32 v206, v214, v215
	v_cvt_pk_bf16_f32 v207, v216, v217
	v_cvt_pk_bf16_f32 v208, v218, v221
	v_cvt_pk_bf16_f32 v209, v222, v223
	v_cvt_pk_bf16_f32 v210, v224, v225
	v_cvt_pk_bf16_f32 v211, v226, v227
	v_cvt_pk_bf16_f32 v212, v132, v133
	v_cvt_pk_bf16_f32 v213, v134, v135
	v_cvt_pk_bf16_f32 v214, v136, v137
	v_cvt_pk_bf16_f32 v215, v138, v139
	v_cvt_pk_bf16_f32 v222, v141, v142
	v_cvt_pk_bf16_f32 v223, v143, v144
	v_cvt_pk_bf16_f32 v224, v145, v146
	v_cvt_pk_bf16_f32 v225, v147, v140
	s_nop 0
	v_permlane32_swap_b32_e32 v204, v206
	v_permlane32_swap_b32_e32 v205, v207
	v_permlane32_swap_b32_e32 v208, v210
	v_permlane32_swap_b32_e32 v209, v211
	v_permlane32_swap_b32_e32 v212, v214
	v_permlane32_swap_b32_e32 v213, v215
	v_permlane32_swap_b32_e32 v222, v224
	v_permlane32_swap_b32_e32 v223, v225
	s_min_u32 s6, s16, s90
	s_add_i32 s6, s6, s88
	s_lshl_b32 s6, s6, 6
	v_add_u32_e32 v132, s6, v167
	v_add_u32_e32 v134, s6, v185
	v_ashrrev_i32_e32 v133, 31, v132
	v_ashrrev_i32_e32 v135, 31, v134
	v_lshlrev_b64 v[140:141], 8, v[132:133]
	v_lshlrev_b64 v[142:143], 8, v[134:135]
	v_or_b32_e32 v140, v140, v182
	v_or_b32_e32 v142, v142, v182
	v_lshl_add_u64 v[132:133], s[58:59], 0, v[140:141]
	v_lshl_add_u64 v[134:135], s[58:59], 0, v[142:143]
	v_lshl_add_u64 v[140:141], s[64:65], 0, v[140:141]
	v_lshl_add_u64 v[142:143], s[64:65], 0, v[142:143]
	global_load_dwordx4 v[136:139], v[132:133], off
	s_nop 0
	global_load_dwordx4 v[132:135], v[134:135], off
	s_nop 0
	global_load_dwordx4 v[144:147], v[140:141], off
	s_nop 0
	global_load_dwordx4 v[140:143], v[142:143], off
	s_waitcnt lgkmcnt(8)
	v_mfma_f32_32x32x16_bf16 v[52:67], v[204:207], v[230:233], v[52:67]
	ds_read_b64_tr_b16 v[250:251], v254 offset:4608
	ds_read_b64_tr_b16 v[252:253], v254 offset:6656
	s_waitcnt lgkmcnt(8)
	v_mfma_f32_32x32x16_bf16 v[52:67], v[208:211], v[234:237], v[52:67]
	ds_read_b64_tr_b16 v[230:231], v254 offset:8704
	ds_read_b64_tr_b16 v[232:233], v254 offset:10752
	s_waitcnt lgkmcnt(8)
	v_mfma_f32_32x32x16_bf16 v[52:67], v[212:215], v[238:241], v[52:67]
	ds_read_b64_tr_b16 v[234:235], v254 offset:12800
	ds_read_b64_tr_b16 v[236:237], v254 offset:14848
	s_waitcnt lgkmcnt(8)
	v_mfma_f32_32x32x16_bf16 v[52:67], v[222:225], v[242:245], v[52:67]
	ds_read_b64_tr_b16 v[238:239], v254 offset:1024
	ds_read_b64_tr_b16 v[240:241], v254 offset:3072
	s_waitcnt lgkmcnt(8)
	v_mfma_f32_32x32x16_bf16 v[36:51], v[204:207], v[246:249], v[36:51]
	ds_read_b64_tr_b16 v[242:243], v254 offset:5120
	ds_read_b64_tr_b16 v[244:245], v254 offset:7168
	s_waitcnt lgkmcnt(8)
	v_mfma_f32_32x32x16_bf16 v[36:51], v[208:211], v[250:253], v[36:51]
	ds_read_b64_tr_b16 v[246:247], v254 offset:9216
	ds_read_b64_tr_b16 v[248:249], v254 offset:11264
	s_waitcnt lgkmcnt(8)
	v_mfma_f32_32x32x16_bf16 v[36:51], v[212:215], v[230:233], v[36:51]
	ds_read_b64_tr_b16 v[250:251], v254 offset:13312
	ds_read_b64_tr_b16 v[252:253], v254 offset:15360
	s_waitcnt lgkmcnt(8)
; #define SBAR() __builtin_amdgcn_sched_barrier(0)
; __device__ __forceinline__ void partialSM(f32x16& p0, f32x16& p1, float& m_reg, float& mn, float& alpha) {
;   constexpr float C = SCALE * 1.4426950408889634f;
;   float pmax = p0[0]; for (int r = 1; r < 16; ++r) pmax = fmaxf(pmax, p0[r]); for (int r = 0; r < 16; ++r) pmax = fmaxf(pmax, p1[r]);
;   { auto rr = __builtin_amdgcn_permlane32_swap(__float_as_uint(pmax), __float_as_uint(pmax), false, false);
;     pmax = fmaxf(__uint_as_float(rr[0]), __uint_as_float(rr[1])); }
;   if (__builtin_expect(__all(pmax - m_reg <= THR / SCALE), 1)) { mn = m_reg; alpha = 1.f; }
;   else { mn = fmaxf(m_reg, pmax); alpha = __builtin_amdgcn_exp2f((m_reg - mn) * C); m_reg = mn; }
; template <int D0> __device__ __forceinline__ void pv_one(f32x16& od, int vb, bf16x8 pa0, bf16x8 pa1, bf16x8 pa2, bf16x8 pa3) {
;   const s16x4 l0 = tr_read<v_rd_off(D0, 0, 0)>(vb), h0 = tr_read<v_rd_off(D0, 0, 1)>(vb), l1 = tr_read<v_rd_off(D0, 1, 0)>(vb), h1 = tr_read<v_rd_off(D0, 1, 1)>(vb);
;   const s16x4 l2 = tr_read<v_rd_off(D0, 2, 0)>(vb), h2 = tr_read<v_rd_off(D0, 2, 1)>(vb), l3 = tr_read<v_rd_off(D0, 3, 0)>(vb), h3 = tr_read<v_rd_off(D0, 3, 1)>(vb);
;   asm volatile("s_waitcnt lgkmcnt(0)" ::: "memory"); SBAR();
;     ...
;   od = __builtin_amdgcn_mfma_f32_32x32x16_bf16(pa0, PK(l0, h0), od, 0, 0, 0);
;   od = __builtin_amdgcn_mfma_f32_32x32x16_bf16(pa1, PK(l1, h1), od, 0, 0, 0);
;   od = __builtin_amdgcn_mfma_f32_32x32x16_bf16(pa2, PK(l2, h2), od, 0, 0, 0);
;   od = __builtin_amdgcn_mfma_f32_32x32x16_bf16(pa3, PK(l3, h3), od, 0, 0, 0);
;     ...
; }
; __device__ __forceinline__ void pv_d0(f32x16* o, int vb, bf16x8 pa0, bf16x8 pa1, bf16x8 pa2, bf16x8 pa3) {
;   pv_one<0>(o[0], vb, pa0, pa1, pa2, pa3); pv_one<1>(o[1], vb, pa0, pa1, pa2, pa3); pv_one<2>(o[2], vb, pa0, pa1, pa2, pa3); pv_one<3>(o[3], vb, pa0, pa1, pa2, pa3);
	v_mfma_f32_32x32x16_bf16 v[36:51], v[222:225], v[234:237], v[36:51]
	ds_read_b64_tr_b16 v[230:231], v254 offset:1536
	ds_read_b64_tr_b16 v[232:233], v254 offset:3584
	s_waitcnt lgkmcnt(8)
	v_mfma_f32_32x32x16_bf16 v[20:35], v[204:207], v[238:241], v[20:35]
	ds_read_b64_tr_b16 v[234:235], v254 offset:5632
	ds_read_b64_tr_b16 v[236:237], v254 offset:7680
	s_waitcnt lgkmcnt(8)
	v_mfma_f32_32x32x16_bf16 v[20:35], v[208:211], v[242:245], v[20:35]
	ds_read_b64_tr_b16 v[238:239], v254 offset:9728
	ds_read_b64_tr_b16 v[240:241], v254 offset:11776
	s_waitcnt lgkmcnt(8)
	v_mfma_f32_32x32x16_bf16 v[20:35], v[212:215], v[246:249], v[20:35]
	ds_read_b64_tr_b16 v[242:243], v254 offset:13824
	ds_read_b64_tr_b16 v[244:245], v254 offset:15872
	s_waitcnt lgkmcnt(8)
	v_mfma_f32_32x32x16_bf16 v[20:35], v[222:225], v[250:253], v[20:35]
	v_max_f32_e32 v166, v85, v85
	v_max_f32_e32 v203, v84, v84
	v_max_f32_e32 v166, v203, v166
	s_waitcnt lgkmcnt(6)
	v_mfma_f32_32x32x16_bf16 v[4:19], v[204:207], v[230:233], v[4:19]
	v_max3_f32 v166, v166, v86, v87
	v_max3_f32 v166, v166, v88, v89
	v_max3_f32 v166, v166, v90, v91
	v_max3_f32 v166, v166, v92, v93
	v_max3_f32 v166, v166, v94, v95
	v_max3_f32 v166, v166, v96, v97
	v_max3_f32 v166, v166, v98, v99
	v_max3_f32 v166, v166, v68, v69
	s_waitcnt lgkmcnt(4)
	v_mfma_f32_32x32x16_bf16 v[4:19], v[208:211], v[234:237], v[4:19]
	v_max3_f32 v166, v166, v70, v71
	v_max3_f32 v166, v166, v72, v73
	v_max3_f32 v166, v166, v74, v75
	v_max3_f32 v166, v166, v76, v77
	v_max3_f32 v166, v166, v78, v79
	v_max3_f32 v166, v166, v80, v81
	v_max3_f32 v166, v166, v82, v83
	v_mov_b32_e32 v203, v166
	s_waitcnt lgkmcnt(2)
	v_mfma_f32_32x32x16_bf16 v[4:19], v[212:215], v[238:241], v[4:19]
	s_nop 0
	v_permlane32_swap_b32_e32 v166, v203
	v_max_f32_e32 v203, v203, v203
	v_max_f32_e32 v166, v166, v166
	v_max_f32_e32 v166, v166, v203
	v_sub_f32_e32 v203, v166, v2
	v_cmp_ge_f32_e32 vcc, s74, v203
	v_max_f32_e32 v203, v2, v2
	v_max_f32_e32 v166, v203, v166
	v_sub_f32_e32 v203, v2, v166
	v_mul_f32_e32 v203, 0x3e0293ee, v203
	s_waitcnt lgkmcnt(0)
	v_mfma_f32_32x32x16_bf16 v[4:19], v[222:225], v[242:245], v[4:19]
	v_exp_f32_e32 v203, v203
	s_cmp_eq_u64 vcc, exec
	s_cselect_b64 s[6:7], -1, 0
	s_add_i32 s30, s94, 0
	v_cndmask_b32_e64 v221, v203, 1.0, s[6:7]
	v_add_u32_e32 v203, s30, v184
	s_waitcnt vmcnt(4)
	s_waitcnt vmcnt(7)
	ds_write_b128 v203, v[152:155]
	v_add_u32_e32 v152, s30, v186
	s_waitcnt vmcnt(6)
	ds_write_b128 v152, v[148:151]
	v_add_u32_e32 v148, s30, v187
	s_waitcnt vmcnt(5)
	ds_write_b128 v148, v[160:163] offset:49152
	v_add_u32_e32 v148, s30, v188
	v_cmp_gt_f32_e32 vcc, 1.0, v221
	s_waitcnt vmcnt(4)
	ds_write_b128 v148, v[156:159] offset:49152
	s_cbranch_vccz .LBB0_482
	s_and_saveexec_b64 s[66:67], s[4:5]
	ds_write_b32 v183, v221 offset:128
	s_or_b64 exec, exec, s[66:67]
	s_waitcnt lgkmcnt(0)
	v_add_u32_e32 v160, v181, v180
	ds_read_b128 v[148:151], v160 offset:224
	ds_read_b128 v[152:155], v160 offset:192
	ds_read_b128 v[156:159], v160 offset:160
	ds_read_b128 v[160:163], v160 offset:128
	s_waitcnt lgkmcnt(3)
	v_pk_mul_f32 v[64:65], v[64:65], v[148:149]
	s_waitcnt lgkmcnt(2)
	v_pk_mul_f32 v[60:61], v[60:61], v[152:153]
	s_waitcnt lgkmcnt(1)
	v_pk_mul_f32 v[56:57], v[56:57], v[156:157]
	v_pk_mul_f32 v[66:67], v[66:67], v[150:151]
	v_pk_mul_f32 v[62:63], v[62:63], v[154:155]
	v_pk_mul_f32 v[58:59], v[58:59], v[158:159]
	s_waitcnt lgkmcnt(0)
	v_pk_mul_f32 v[54:55], v[54:55], v[162:163]
	v_pk_mul_f32 v[52:53], v[52:53], v[160:161]
	v_pk_mul_f32 v[48:49], v[48:49], v[148:149]
	v_pk_mul_f32 v[44:45], v[44:45], v[152:153]
	v_pk_mul_f32 v[40:41], v[40:41], v[156:157]
	v_pk_mul_f32 v[50:51], v[50:51], v[150:151]
	v_pk_mul_f32 v[46:47], v[46:47], v[154:155]
	v_pk_mul_f32 v[42:43], v[42:43], v[158:159]
	v_pk_mul_f32 v[38:39], v[38:39], v[162:163]
	v_pk_mul_f32 v[36:37], v[36:37], v[160:161]
	v_pk_mul_f32 v[32:33], v[32:33], v[148:149]
	v_pk_mul_f32 v[28:29], v[28:29], v[152:153]
	v_pk_mul_f32 v[24:25], v[24:25], v[156:157]
	v_pk_mul_f32 v[34:35], v[34:35], v[150:151]
	v_pk_mul_f32 v[30:31], v[30:31], v[154:155]
	v_pk_mul_f32 v[26:27], v[26:27], v[158:159]
	v_pk_mul_f32 v[22:23], v[22:23], v[162:163]
	v_pk_mul_f32 v[20:21], v[20:21], v[160:161]
	v_pk_mul_f32 v[16:17], v[16:17], v[148:149]
	v_pk_mul_f32 v[12:13], v[12:13], v[152:153]
	v_pk_mul_f32 v[8:9], v[8:9], v[156:157]
	v_pk_mul_f32 v[18:19], v[18:19], v[150:151]
	v_pk_mul_f32 v[14:15], v[14:15], v[154:155]
	v_pk_mul_f32 v[10:11], v[10:11], v[158:159]
	v_pk_mul_f32 v[6:7], v[6:7], v[162:163]
	v_pk_mul_f32 v[4:5], v[4:5], v[160:161]

; #define SBAR() __builtin_amdgcn_sched_barrier(0)
; #define QKT(P0, P1, KS) do { if (MODE == 1) qkt_lds(P0, P1, KS, qs, r32, hi); else qkt(P0, P1, KS, qr, r32, hi); } while (0)
; __device__ __forceinline__ void finishSM(f32x16& p0, f32x16& p1, float alpha, float& l_reg, bf16x8& pa0, bf16x8& pa1, bf16x8& pa2, bf16x8& pa3) {
;   for (int r = 0; r < 16; ++r) p1[r] = __builtin_amdgcn_exp2f(p1[r]);
;   float ps = 0; for (int r = 0; r < 16; ++r) ps += p0[r]; for (int r = 0; r < 16; ++r) ps += p1[r];
;   { auto rr = __builtin_amdgcn_permlane32_swap(__float_as_uint(ps), __float_as_uint(ps), false, false);
;     ps = __uint_as_float(rr[0]) + __uint_as_float(rr[1]); }
;   l_reg = l_reg * alpha + ps;
;     ...
;   PK4(p0, 0, pa0); PK4(p0, 8, pa1); PK4(p1, 0, pa2); PK4(p1, 8, pa3);
;     ...
; }
; __device__ __forceinline__ void qkt(f32x16& p0, f32x16& p1, const u16* Ks, const bf16x8* qr, int r32, int hi) {
;   p0 = f32x16{}; p1 = f32x16{};
;   for (int d0 = 0; d0 < 8; ++d0) { int cb = (d0 * 16 + hi * 8) * 2;
;     bf16x8 b0 = *reinterpret_cast<const bf16x8*>((const char*)Ks + KSWZ(r32, cb));
;     bf16x8 b1 = *reinterpret_cast<const bf16x8*>((const char*)Ks + KSWZ(32 + r32, cb));
;     p0 = __builtin_amdgcn_mfma_f32_32x32x16_bf16(b0, qr[d0], p0, 0, 0, 0);
;     p1 = __builtin_amdgcn_mfma_f32_32x32x16_bf16(b1, qr[d0], p1, 0, 0, 0); }
; }
; template <int MODE> ...
;     ...
;     for (int j = 1; j + 1 < NT; j += 2) {
;       const int s0_ = sj, s1_ = sj == 2 ? 0 : sj + 1, s2_ = s1_ == 2 ? 0 : s1_ + 1;
;       SBAR(); QKT(pB0, pB1, (u16*)((char*)K_lds + s0_ * SHM_K));
;       finishSM(pA0, pA1, alA, l_reg, pa0, pa1, pa2, pa3); SBAR();
;       { const int tn = (j + 2 < NT) ? j + 2 : NT - 1; SLOAD(SO, tn); } SBAR();
;       pv_d0(o, vb0 + s2_ * (int)SHM_V, pa0, pa1, pa2, pa3); partialSM(pB0, pB1, m_reg, mnB, alB);
.Lstg_loop:
	s_add_i32 s7, s89, 1
	s_cmp_lg_u32 s89, 2
	s_cselect_b32 s66, s7, 0
	s_add_i32 s7, s66, 1
	s_cmp_lg_u32 s66, 2
	s_mov_b32 s6, s89
	s_cselect_b32 s89, s7, 0
	s_lshl_b32 s93, s6, 14
	s_add_i32 s6, s93, 0
	v_add_u32_e32 v254, s6, v189
	ds_read_b128 v[68:71], v254 offset:49152
	ds_read_b128 v[72:75], v254 offset:57344
	v_add_u32_e32 v254, s6, v190
	ds_read_b128 v[220:223], v254 offset:49152
	ds_read_b128 v[224:227], v254 offset:57344
	v_add_u32_e32 v254, s6, v191
	ds_read_b128 v[228:231], v254 offset:49152
	ds_read_b128 v[232:235], v254 offset:57344
	v_add_u32_e32 v254, s6, v192
	ds_read_b128 v[236:239], v254 offset:49152
	ds_read_b128 v[240:243], v254 offset:57344
	v_add_u32_e32 v254, s6, v193
	ds_read_b128 v[246:249], v254 offset:49152
	ds_read_b128 v[250:253], v254 offset:57344
	s_waitcnt lgkmcnt(9)
	v_mfma_f32_32x32x16_bf16 v[84:99], v[68:71], v[100:103], 0
	v_exp_f32_e32 v160, v160
	v_exp_f32_e32 v161, v161
	v_exp_f32_e32 v158, v158
	v_exp_f32_e32 v159, v159
	v_exp_f32_e32 v156, v156
	v_exp_f32_e32 v157, v157
	v_exp_f32_e32 v154, v154
	s_waitcnt lgkmcnt(8)
	v_mfma_f32_32x32x16_bf16 v[68:83], v[72:75], v[100:103], 0
	v_exp_f32_e32 v155, v155
	v_exp_f32_e32 v152, v152
	v_exp_f32_e32 v153, v153
	v_exp_f32_e32 v150, v150
	v_exp_f32_e32 v151, v151
	v_exp_f32_e32 v148, v148
	v_exp_f32_e32 v149, v149
	s_waitcnt lgkmcnt(7)
	v_mfma_f32_32x32x16_bf16 v[84:99], v[220:223], v[104:107], v[84:99]
	s_waitcnt lgkmcnt(6)
	v_mfma_f32_32x32x16_bf16 v[68:83], v[224:227], v[104:107], v[68:83]
	v_add_u32_e32 v254, s6, v194
	ds_read_b128 v[220:223], v254 offset:49152
	ds_read_b128 v[224:227], v254 offset:57344
	s_waitcnt lgkmcnt(7)
	v_mfma_f32_32x32x16_bf16 v[84:99], v[228:231], v[108:111], v[84:99]
	s_waitcnt lgkmcnt(6)
	v_mfma_f32_32x32x16_bf16 v[68:83], v[232:235], v[108:111], v[68:83]
	v_add_u32_e32 v254, s6, v195
	ds_read_b128 v[228:231], v254 offset:49152
	ds_read_b128 v[232:235], v254 offset:57344
	s_waitcnt lgkmcnt(7)
	v_mfma_f32_32x32x16_bf16 v[84:99], v[236:239], v[112:115], v[84:99]
	s_waitcnt lgkmcnt(6)
	v_mfma_f32_32x32x16_bf16 v[68:83], v[240:243], v[112:115], v[68:83]
	v_add_u32_e32 v254, s6, v196
	ds_read_b128 v[236:239], v254 offset:49152
	ds_read_b128 v[240:243], v254 offset:57344
	s_waitcnt lgkmcnt(7)
	v_mfma_f32_32x32x16_bf16 v[84:99], v[246:249], v[116:119], v[84:99]
	s_waitcnt lgkmcnt(6)
	v_mfma_f32_32x32x16_bf16 v[68:83], v[250:253], v[116:119], v[68:83]
	s_waitcnt lgkmcnt(5)
	v_mfma_f32_32x32x16_bf16 v[84:99], v[220:223], v[120:123], v[84:99]
	s_waitcnt lgkmcnt(4)
	v_mfma_f32_32x32x16_bf16 v[68:83], v[224:227], v[120:123], v[68:83]
	s_waitcnt lgkmcnt(3)
	v_mfma_f32_32x32x16_bf16 v[84:99], v[228:231], v[124:127], v[84:99]
	s_waitcnt lgkmcnt(2)
	v_mfma_f32_32x32x16_bf16 v[68:83], v[232:235], v[124:127], v[68:83]
	v_exp_f32_e32 v2, v162
	v_exp_f32_e32 v162, v163
	v_add_f32_e32 v163, 0, v216
	v_add_f32_e32 v163, v218, v163
	v_add_f32_e32 v163, v214, v163
	v_add_f32_e32 v163, v217, v163
	v_add_f32_e32 v163, v213, v163
	v_add_f32_e32 v163, v215, v163
	v_add_f32_e32 v163, v211, v163
	v_add_f32_e32 v163, v212, v163
	v_add_f32_e32 v163, v208, v163
	v_add_f32_e32 v163, v210, v163
	v_add_f32_e32 v163, v207, v163
	v_add_f32_e32 v163, v209, v163
	v_add_f32_e32 v163, v204, v163
	v_add_f32_e32 v163, v206, v163
	v_add_f32_e32 v163, v203, v163
	v_add_f32_e32 v163, v205, v163
	v_add_f32_e32 v163, v2, v163
	v_add_f32_e32 v163, v162, v163
	v_add_f32_e32 v163, v160, v163
	v_add_f32_e32 v163, v161, v163
	v_add_f32_e32 v163, v158, v163
	v_add_f32_e32 v163, v159, v163
	v_add_f32_e32 v163, v156, v163
	v_add_f32_e32 v163, v157, v163
	v_add_f32_e32 v163, v154, v163
	v_add_f32_e32 v163, v155, v163
	s_waitcnt lgkmcnt(1)
	v_mfma_f32_32x32x16_bf16 v[84:99], v[236:239], v[128:131], v[84:99]
	v_add_f32_e32 v163, v152, v163
	v_add_f32_e32 v163, v153, v163
	v_add_f32_e32 v163, v150, v163
	v_add_f32_e32 v163, v151, v163
	v_add_f32_e32 v163, v148, v163
	v_add_f32_e32 v200, v149, v163
	v_mov_b32_e32 v201, v200
	s_waitcnt lgkmcnt(0)
	v_mfma_f32_32x32x16_bf16 v[68:83], v[240:243], v[128:131], v[68:83]
	s_lshl_b32 s94, s89, 14
	v_add_u32_e32 v254, s94, v197
	ds_read_b64_tr_b16 v[220:221], v254 offset:0
	ds_read_b64_tr_b16 v[222:223], v254 offset:2048
	ds_read_b64_tr_b16 v[224:225], v254 offset:4096
	ds_read_b64_tr_b16 v[226:227], v254 offset:6144
	ds_read_b64_tr_b16 v[228:229], v254 offset:8192
	ds_read_b64_tr_b16 v[230:231], v254 offset:10240
	ds_read_b64_tr_b16 v[232:233], v254 offset:12288
	ds_read_b64_tr_b16 v[234:235], v254 offset:14336
	ds_read_b64_tr_b16 v[236:237], v254 offset:512
	ds_read_b64_tr_b16 v[238:239], v254 offset:2560
	v_cvt_pk_bf16_f32 v216, v216, v218
	v_cvt_pk_bf16_f32 v217, v214, v217
	v_cvt_pk_bf16_f32 v218, v213, v215
	v_cvt_pk_bf16_f32 v219, v211, v212
	v_cvt_pk_bf16_f32 v208, v208, v210
	v_cvt_pk_bf16_f32 v209, v207, v209
	v_cvt_pk_bf16_f32 v210, v204, v206
	v_cvt_pk_bf16_f32 v211, v203, v205
	v_cvt_pk_bf16_f32 v202, v2, v162
	v_cvt_pk_bf16_f32 v203, v160, v161
	v_cvt_pk_bf16_f32 v204, v158, v159
	v_permlane32_swap_b32_e32 v200, v201
	v_cvt_pk_bf16_f32 v205, v156, v157
	v_permlane32_swap_b32_e32 v202, v204
	v_cvt_pk_bf16_f32 v212, v154, v155
	v_cvt_pk_bf16_f32 v213, v152, v153
	v_cvt_pk_bf16_f32 v214, v150, v151
	v_cvt_pk_bf16_f32 v215, v148, v149
	v_permlane32_swap_b32_e32 v216, v218
	v_permlane32_swap_b32_e32 v217, v219
	v_permlane32_swap_b32_e32 v208, v210
	v_permlane32_swap_b32_e32 v209, v211
	v_permlane32_swap_b32_e32 v203, v205
	v_permlane32_swap_b32_e32 v212, v214
	v_permlane32_swap_b32_e32 v213, v215
	s_add_i32 s91, s16, -1
	s_min_u32 s6, s91, s90
	s_add_i32 s6, s6, s88
	s_lshl_b32 s6, s6, 6
	v_add_u32_e32 v148, s6, v167
	v_add_u32_e32 v150, s6, v185
	v_ashrrev_i32_e32 v149, 31, v148
	v_ashrrev_i32_e32 v151, 31, v150
	v_lshlrev_b64 v[156:157], 8, v[148:149]
	v_lshlrev_b64 v[158:159], 8, v[150:151]
	v_or_b32_e32 v156, v156, v182
	v_or_b32_e32 v158, v158, v182
	v_lshl_add_u64 v[148:149], s[58:59], 0, v[156:157]
	v_lshl_add_u64 v[150:151], s[58:59], 0, v[158:159]
	v_lshl_add_u64 v[156:157], s[64:65], 0, v[156:157]
	v_lshl_add_u64 v[158:159], s[64:65], 0, v[158:159]
	global_load_dwordx4 v[152:155], v[148:149], off
	s_nop 0
	global_load_dwordx4 v[148:151], v[150:151], off
	s_nop 0
	global_load_dwordx4 v[160:163], v[156:157], off
	s_nop 0
	global_load_dwordx4 v[156:159], v[158:159], off
	s_waitcnt lgkmcnt(8)
; #define SBAR() __builtin_amdgcn_sched_barrier(0)
; #define SWRITE(b, i) do { *(bf16x8*)((char*)V_lds + (b) * SHM_V + vst0) = sr_[i].vs0;          \
;     *(bf16x8*)((char*)V_lds + (b) * SHM_V + vst1) = sr_[i].vs1; int kc = sc * 2;               \
;     *(bf16x8*)((char*)K_lds + (b) * SHM_K + KSWZ(sr, kc)) = sr_[i].ks0;                       \
;     *(bf16x8*)((char*)K_lds + (b) * SHM_K + KSWZ(32 + sr, kc)) = sr_[i].ks1; } while (0)
; #define SWAIT() do { if (SD == 2) asm volatile("s_waitcnt vmcnt(4)" ::: "memory"); else asm volatile("s_waitcnt vmcnt(0)" ::: "memory"); } while (0)
; #define RESC(a) do { if (__any((a) < 1.f)) { if (hi == 0) al_l[r32] = (a); asm volatile("s_waitcnt lgkmcnt(0)" ::: "memory"); \
;     for (int d = 0; d < 4; ++d) for (int r = 0; r < 16; ++r) o[d][r] *= al_l[crow(r, hi)]; } } while (0)
; template <int D0> __device__ __forceinline__ void pv_one(f32x16& od, int vb, bf16x8 pa0, bf16x8 pa1, bf16x8 pa2, bf16x8 pa3) {
;   const s16x4 l0 = tr_read<v_rd_off(D0, 0, 0)>(vb), h0 = tr_read<v_rd_off(D0, 0, 1)>(vb), l1 = tr_read<v_rd_off(D0, 1, 0)>(vb), h1 = tr_read<v_rd_off(D0, 1, 1)>(vb);
;   const s16x4 l2 = tr_read<v_rd_off(D0, 2, 0)>(vb), h2 = tr_read<v_rd_off(D0, 2, 1)>(vb), l3 = tr_read<v_rd_off(D0, 3, 0)>(vb), h3 = tr_read<v_rd_off(D0, 3, 1)>(vb);
;   asm volatile("s_waitcnt lgkmcnt(0)" ::: "memory"); SBAR();
;     ...
;   od = __builtin_amdgcn_mfma_f32_32x32x16_bf16(pa0, PK(l0, h0), od, 0, 0, 0);
;   od = __builtin_amdgcn_mfma_f32_32x32x16_bf16(pa1, PK(l1, h1), od, 0, 0, 0);
;   od = __builtin_amdgcn_mfma_f32_32x32x16_bf16(pa2, PK(l2, h2), od, 0, 0, 0);
;   od = __builtin_amdgcn_mfma_f32_32x32x16_bf16(pa3, PK(l3, h3), od, 0, 0, 0);
;     ...
; }
; __device__ __forceinline__ void pv_d0(f32x16* o, int vb, bf16x8 pa0, bf16x8 pa1, bf16x8 pa2, bf16x8 pa3) {
;   pv_one<0>(o[0], vb, pa0, pa1, pa2, pa3); pv_one<1>(o[1], vb, pa0, pa1, pa2, pa3); pv_one<2>(o[2], vb, pa0, pa1, pa2, pa3); pv_one<3>(o[3], vb, pa0, pa1, pa2, pa3);
; template <int MODE> ...
;     ...
;       pv_d0(o, vb0 + s2_ * (int)SHM_V, pa0, pa1, pa2, pa3); partialSM(pB0, pB1, m_reg, mnB, alB);
;       SWAIT(); SWRITE(s1_, SE);
;       RESC(alB); __syncthreads();
	v_mfma_f32_32x32x16_bf16 v[52:67], v[216:219], v[220:223], v[52:67]
	ds_read_b64_tr_b16 v[240:241], v254 offset:4608
	ds_read_b64_tr_b16 v[242:243], v254 offset:6656
	s_waitcnt lgkmcnt(8)
	v_mfma_f32_32x32x16_bf16 v[52:67], v[208:211], v[224:227], v[52:67]
	ds_read_b64_tr_b16 v[220:221], v254 offset:8704
	ds_read_b64_tr_b16 v[222:223], v254 offset:10752
	s_waitcnt lgkmcnt(8)
	v_mfma_f32_32x32x16_bf16 v[52:67], v[202:205], v[228:231], v[52:67]
	ds_read_b64_tr_b16 v[224:225], v254 offset:12800
	ds_read_b64_tr_b16 v[226:227], v254 offset:14848
	s_waitcnt lgkmcnt(8)
	v_mfma_f32_32x32x16_bf16 v[52:67], v[212:215], v[232:235], v[52:67]
	ds_read_b64_tr_b16 v[228:229], v254 offset:1024
	ds_read_b64_tr_b16 v[230:231], v254 offset:3072
	s_waitcnt lgkmcnt(8)
	v_mfma_f32_32x32x16_bf16 v[36:51], v[216:219], v[236:239], v[36:51]
	ds_read_b64_tr_b16 v[232:233], v254 offset:5120
	ds_read_b64_tr_b16 v[234:235], v254 offset:7168
	s_waitcnt lgkmcnt(8)
	v_mfma_f32_32x32x16_bf16 v[36:51], v[208:211], v[240:243], v[36:51]
	ds_read_b64_tr_b16 v[236:237], v254 offset:9216
	ds_read_b64_tr_b16 v[238:239], v254 offset:11264
	s_waitcnt lgkmcnt(8)
	v_mfma_f32_32x32x16_bf16 v[36:51], v[202:205], v[220:223], v[36:51]
	ds_read_b64_tr_b16 v[240:241], v254 offset:13312
	ds_read_b64_tr_b16 v[242:243], v254 offset:15360
	s_waitcnt lgkmcnt(8)
	v_mfma_f32_32x32x16_bf16 v[36:51], v[212:215], v[224:227], v[36:51]
	ds_read_b64_tr_b16 v[220:221], v254 offset:1536
	ds_read_b64_tr_b16 v[222:223], v254 offset:3584
	s_waitcnt lgkmcnt(8)
	v_mfma_f32_32x32x16_bf16 v[20:35], v[216:219], v[228:231], v[20:35]
	ds_read_b64_tr_b16 v[224:225], v254 offset:5632
	ds_read_b64_tr_b16 v[226:227], v254 offset:7680
	s_waitcnt lgkmcnt(8)
	v_mfma_f32_32x32x16_bf16 v[20:35], v[208:211], v[232:235], v[20:35]
	ds_read_b64_tr_b16 v[228:229], v254 offset:9728
	ds_read_b64_tr_b16 v[230:231], v254 offset:11776
	s_waitcnt lgkmcnt(8)
	v_mfma_f32_32x32x16_bf16 v[20:35], v[202:205], v[236:239], v[20:35]
	ds_read_b64_tr_b16 v[232:233], v254 offset:13824
	ds_read_b64_tr_b16 v[234:235], v254 offset:15872
	s_waitcnt lgkmcnt(8)
	v_mfma_f32_32x32x16_bf16 v[20:35], v[212:215], v[240:243], v[20:35]
	s_waitcnt lgkmcnt(6)
	v_mfma_f32_32x32x16_bf16 v[4:19], v[216:219], v[220:223], v[4:19]
	s_waitcnt vmcnt(4)
	s_waitcnt lgkmcnt(4)
	v_mfma_f32_32x32x16_bf16 v[4:19], v[208:211], v[224:227], v[4:19]
	s_waitcnt lgkmcnt(2)
	v_mfma_f32_32x32x16_bf16 v[4:19], v[202:205], v[228:231], v[4:19]
	s_waitcnt lgkmcnt(0)
	v_mfma_f32_32x32x16_bf16 v[4:19], v[212:215], v[232:235], v[4:19]
	s_lshl_b32 s92, s66, 14
	s_add_i32 s95, s92, 0
	v_add_u32_e32 v203, s95, v184
	s_waitcnt vmcnt(7)
	ds_write_b128 v203, v[136:139]
	v_add_u32_e32 v136, s95, v186
	s_waitcnt vmcnt(6)
	ds_write_b128 v136, v[132:135]
	v_add_u32_e32 v132, s95, v187
	s_waitcnt vmcnt(5)
	ds_write_b128 v132, v[144:147] offset:49152
	v_add_u32_e32 v132, s95, v188
	s_waitcnt vmcnt(4)
	ds_write_b128 v132, v[140:143] offset:49152
	s_waitcnt lgkmcnt(0)
	s_barrier
	v_max_f32_e32 v2, v85, v85
	v_max_f32_e32 v202, v84, v84
	v_max_f32_e32 v2, v202, v2
	v_max3_f32 v2, v2, v86, v87
	v_max3_f32 v2, v2, v88, v89
	v_max3_f32 v2, v2, v90, v91
	v_max3_f32 v2, v2, v92, v93
	v_max3_f32 v2, v2, v94, v95
	v_max3_f32 v2, v2, v96, v97
	v_max3_f32 v2, v2, v98, v99
	v_max3_f32 v2, v2, v68, v69
	v_max3_f32 v2, v2, v70, v71
	v_max3_f32 v2, v2, v72, v73
	v_max3_f32 v2, v2, v74, v75
	v_max3_f32 v2, v2, v76, v77
	v_max3_f32 v2, v2, v78, v79
	v_max3_f32 v2, v2, v80, v81
	v_max3_f32 v2, v2, v82, v83
	v_mov_b32_e32 v202, v2
	s_nop 1
	v_permlane32_swap_b32_e32 v2, v202
	v_max_f32_e32 v202, v202, v202
	v_max_f32_e32 v2, v2, v2
	v_max_f32_e32 v2, v2, v202
	v_sub_f32_e32 v202, v2, v166
	v_cmp_ge_f32_e32 vcc, s74, v202
	v_max_f32_e32 v202, v166, v166
	v_max_f32_e32 v2, v202, v2
	v_sub_f32_e32 v202, v166, v2
	s_cmp_eq_u64 vcc, exec
	v_mul_f32_e32 v202, 0x3e0293ee, v202
	s_cselect_b64 s[6:7], -1, 0
	v_exp_f32_e32 v202, v202
	s_nop 0
	v_cndmask_b32_e64 v202, v202, 1.0, s[6:7]
	v_cmp_gt_f32_e32 vcc, 1.0, v202
	s_cbranch_vccz .Lstg_r1
	s_and_saveexec_b64 s[66:67], s[4:5]
	ds_write_b32 v183, v202 offset:128
	s_or_b64 exec, exec, s[66:67]
	s_waitcnt lgkmcnt(0)
	v_add_u32_e32 v144, v181, v180
	ds_read_b128 v[132:135], v144 offset:224
	ds_read_b128 v[136:139], v144 offset:192
	ds_read_b128 v[140:143], v144 offset:160
	ds_read_b128 v[144:147], v144 offset:128
	s_waitcnt lgkmcnt(3)
	v_pk_mul_f32 v[64:65], v[64:65], v[132:133]
	s_waitcnt lgkmcnt(2)
	v_pk_mul_f32 v[60:61], v[60:61], v[136:137]
	s_waitcnt lgkmcnt(1)
	v_pk_mul_f32 v[56:57], v[56:57], v[140:141]
	v_pk_mul_f32 v[66:67], v[66:67], v[134:135]
	v_pk_mul_f32 v[62:63], v[62:63], v[138:139]
	v_pk_mul_f32 v[58:59], v[58:59], v[142:143]
	s_waitcnt lgkmcnt(0)
	v_pk_mul_f32 v[54:55], v[54:55], v[146:147]
	v_pk_mul_f32 v[52:53], v[52:53], v[144:145]
	v_pk_mul_f32 v[48:49], v[48:49], v[132:133]
	v_pk_mul_f32 v[44:45], v[44:45], v[136:137]
	v_pk_mul_f32 v[40:41], v[40:41], v[140:141]
	v_pk_mul_f32 v[50:51], v[50:51], v[134:135]
	v_pk_mul_f32 v[46:47], v[46:47], v[138:139]
	v_pk_mul_f32 v[42:43], v[42:43], v[142:143]
	v_pk_mul_f32 v[38:39], v[38:39], v[146:147]
	v_pk_mul_f32 v[36:37], v[36:37], v[144:145]
	v_pk_mul_f32 v[32:33], v[32:33], v[132:133]
	v_pk_mul_f32 v[28:29], v[28:29], v[136:137]
	v_pk_mul_f32 v[24:25], v[24:25], v[140:141]
	v_pk_mul_f32 v[34:35], v[34:35], v[134:135]
	v_pk_mul_f32 v[30:31], v[30:31], v[138:139]
	v_pk_mul_f32 v[26:27], v[26:27], v[142:143]
	v_pk_mul_f32 v[22:23], v[22:23], v[146:147]
	v_pk_mul_f32 v[20:21], v[20:21], v[144:145]
	v_pk_mul_f32 v[16:17], v[16:17], v[132:133]
	v_pk_mul_f32 v[12:13], v[12:13], v[136:137]
	v_pk_mul_f32 v[8:9], v[8:9], v[140:141]
	v_pk_mul_f32 v[18:19], v[18:19], v[134:135]
	v_pk_mul_f32 v[14:15], v[14:15], v[138:139]
	v_pk_mul_f32 v[10:11], v[10:11], v[142:143]
	v_pk_mul_f32 v[6:7], v[6:7], v[146:147]
	v_pk_mul_f32 v[4:5], v[4:5], v[144:145]
; __device__ __forceinline__ void partialSM(f32x16& p0, f32x16& p1, float& m_reg, float& mn, float& alpha) {
;   constexpr float C = SCALE * 1.4426950408889634f;
;   float pmax = p0[0]; for (int r = 1; r < 16; ++r) pmax = fmaxf(pmax, p0[r]); for (int r = 0; r < 16; ++r) pmax = fmaxf(pmax, p1[r]);
;   { auto rr = __builtin_amdgcn_permlane32_swap(__float_as_uint(pmax), __float_as_uint(pmax), false, false);
;     pmax = fmaxf(__uint_as_float(rr[0]), __uint_as_float(rr[1])); }
;   if (__builtin_expect(__all(pmax - m_reg <= THR / SCALE), 1)) { mn = m_reg; alpha = 1.f; }
;   else { mn = fmaxf(m_reg, pmax); alpha = __builtin_amdgcn_exp2f((m_reg - mn) * C); m_reg = mn; }
;   float mnC = -mn * C;
;   for (int r = 0; r < 16; ++r) p0[r] = fmaf(p0[r], C, mnC); for (int r = 0; r < 16; ++r) p1[r] = fmaf(p1[r], C, mnC);
;   for (int r = 0; r < 16; ++r) p0[r] = __builtin_amdgcn_exp2f(p0[r]);
; }
; __device__ __forceinline__ void qkt(f32x16& p0, f32x16& p1, const u16* Ks, const bf16x8* qr, int r32, int hi) {
;   p0 = f32x16{}; p1 = f32x16{};
;   for (int d0 = 0; d0 < 8; ++d0) { int cb = (d0 * 16 + hi * 8) * 2;
;     bf16x8 b0 = *reinterpret_cast<const bf16x8*>((const char*)Ks + KSWZ(r32, cb));
;     bf16x8 b1 = *reinterpret_cast<const bf16x8*>((const char*)Ks + KSWZ(32 + r32, cb));
;     p0 = __builtin_amdgcn_mfma_f32_32x32x16_bf16(b0, qr[d0], p0, 0, 0, 0);
;     p1 = __builtin_amdgcn_mfma_f32_32x32x16_bf16(b1, qr[d0], p1, 0, 0, 0); }
; }
.Lstg_r1:
	v_cndmask_b32_e64 v2, v2, v166, s[6:7]
	v_mul_f32_e32 v140, 0xbe0293ee, v2
	v_fmamk_f32 v93, v93, 0x3e0293ee, v140
	v_exp_f32_e32 v221, v93
	v_fmamk_f32 v84, v84, 0x3e0293ee, v140
	v_fmamk_f32 v85, v85, 0x3e0293ee, v140
	v_fmamk_f32 v86, v86, 0x3e0293ee, v140
	v_fmamk_f32 v87, v87, 0x3e0293ee, v140
	v_fmamk_f32 v88, v88, 0x3e0293ee, v140
	v_fmamk_f32 v89, v89, 0x3e0293ee, v140
	v_fmamk_f32 v90, v90, 0x3e0293ee, v140
	v_fmamk_f32 v91, v91, 0x3e0293ee, v140
	v_fmamk_f32 v92, v92, 0x3e0293ee, v140
	v_fmamk_f32 v94, v94, 0x3e0293ee, v140
	v_fmamk_f32 v95, v95, 0x3e0293ee, v140
	v_fmamk_f32 v96, v96, 0x3e0293ee, v140
	v_fmamk_f32 v97, v97, 0x3e0293ee, v140
	v_fmamk_f32 v98, v98, 0x3e0293ee, v140
	v_fmamk_f32 v99, v99, 0x3e0293ee, v140
	v_fmamk_f32 v141, v68, 0x3e0293ee, v140
	v_fmamk_f32 v142, v69, 0x3e0293ee, v140
	v_fmamk_f32 v143, v70, 0x3e0293ee, v140
	v_fmamk_f32 v144, v71, 0x3e0293ee, v140
	v_fmamk_f32 v145, v72, 0x3e0293ee, v140
	v_fmamk_f32 v146, v73, 0x3e0293ee, v140
	v_fmamk_f32 v147, v74, 0x3e0293ee, v140
	v_fmamk_f32 v166, v75, 0x3e0293ee, v140
	v_fmamk_f32 v203, v76, 0x3e0293ee, v140
	v_fmamk_f32 v204, v77, 0x3e0293ee, v140
	v_fmamk_f32 v205, v78, 0x3e0293ee, v140
	v_fmamk_f32 v206, v79, 0x3e0293ee, v140
	v_fmamk_f32 v207, v80, 0x3e0293ee, v140
	v_fmamk_f32 v208, v81, 0x3e0293ee, v140
	v_fmamk_f32 v209, v82, 0x3e0293ee, v140
	v_fmac_f32_e32 v140, 0x3e0293ee, v83
	v_exp_f32_e32 v210, v84
	v_exp_f32_e32 v211, v85
	v_exp_f32_e32 v212, v86
	v_exp_f32_e32 v213, v87
	v_exp_f32_e32 v214, v88
	v_exp_f32_e32 v215, v89
	v_exp_f32_e32 v216, v90
	v_exp_f32_e32 v217, v91
	v_exp_f32_e32 v218, v92
	v_exp_f32_e32 v222, v94
	v_exp_f32_e32 v223, v95
	v_exp_f32_e32 v224, v96
	v_exp_f32_e32 v225, v97
	v_exp_f32_e32 v226, v98
	v_exp_f32_e32 v227, v99
	v_add_u32_e32 v254, s95, v189
	ds_read_b128 v[68:71], v254 offset:49152
	ds_read_b128 v[72:75], v254 offset:57344
	v_add_u32_e32 v254, s95, v190
	ds_read_b128 v[132:135], v254 offset:49152
	ds_read_b128 v[136:139], v254 offset:57344
	v_add_u32_e32 v254, s95, v191
	ds_read_b128 v[228:231], v254 offset:49152
	ds_read_b128 v[232:235], v254 offset:57344
	v_add_u32_e32 v254, s95, v192
	ds_read_b128 v[236:239], v254 offset:49152
	ds_read_b128 v[240:243], v254 offset:57344
	v_add_u32_e32 v254, s95, v193
	ds_read_b128 v[246:249], v254 offset:49152
	ds_read_b128 v[250:253], v254 offset:57344
	s_waitcnt lgkmcnt(9)
	v_mfma_f32_32x32x16_bf16 v[84:99], v[68:71], v[100:103], 0
	v_exp_f32_e32 v140, v140
	s_waitcnt lgkmcnt(8)
	v_mfma_f32_32x32x16_bf16 v[68:83], v[72:75], v[100:103], 0
	s_waitcnt lgkmcnt(7)
	v_mfma_f32_32x32x16_bf16 v[84:99], v[132:135], v[104:107], v[84:99]
	s_waitcnt lgkmcnt(6)
	v_mfma_f32_32x32x16_bf16 v[68:83], v[136:139], v[104:107], v[68:83]
	v_add_u32_e32 v254, s95, v194
	ds_read_b128 v[132:135], v254 offset:49152
	ds_read_b128 v[136:139], v254 offset:57344
	s_waitcnt lgkmcnt(7)
	v_mfma_f32_32x32x16_bf16 v[84:99], v[228:231], v[108:111], v[84:99]
	s_waitcnt lgkmcnt(6)
	v_mfma_f32_32x32x16_bf16 v[68:83], v[232:235], v[108:111], v[68:83]
	v_add_u32_e32 v254, s95, v195
	ds_read_b128 v[228:231], v254 offset:49152
	ds_read_b128 v[232:235], v254 offset:57344
	s_waitcnt lgkmcnt(7)
	v_mfma_f32_32x32x16_bf16 v[84:99], v[236:239], v[112:115], v[84:99]
	s_waitcnt lgkmcnt(6)
	v_mfma_f32_32x32x16_bf16 v[68:83], v[240:243], v[112:115], v[68:83]
	v_add_u32_e32 v254, s95, v196
	ds_read_b128 v[236:239], v254 offset:49152
	ds_read_b128 v[240:243], v254 offset:57344
	s_waitcnt lgkmcnt(7)
	v_mfma_f32_32x32x16_bf16 v[84:99], v[246:249], v[116:119], v[84:99]
	s_waitcnt lgkmcnt(6)
	v_mfma_f32_32x32x16_bf16 v[68:83], v[250:253], v[116:119], v[68:83]
	s_waitcnt lgkmcnt(5)
	v_mfma_f32_32x32x16_bf16 v[84:99], v[132:135], v[120:123], v[84:99]
	s_waitcnt lgkmcnt(4)
	v_mfma_f32_32x32x16_bf16 v[68:83], v[136:139], v[120:123], v[68:83]
	s_waitcnt lgkmcnt(3)
	v_mfma_f32_32x32x16_bf16 v[84:99], v[228:231], v[124:127], v[84:99]
	s_waitcnt lgkmcnt(2)
	v_mfma_f32_32x32x16_bf16 v[68:83], v[232:235], v[124:127], v[68:83]
	s_waitcnt lgkmcnt(1)
	v_mfma_f32_32x32x16_bf16 v[84:99], v[236:239], v[128:131], v[84:99]
	v_exp_f32_e32 v139, v166
	v_add_f32_e32 v166, 0, v210
	v_add_f32_e32 v166, v211, v166
	v_add_f32_e32 v166, v212, v166
	v_add_f32_e32 v166, v213, v166
	v_add_f32_e32 v166, v214, v166
	v_add_f32_e32 v166, v215, v166
	v_add_f32_e32 v166, v216, v166
	v_add_f32_e32 v166, v217, v166
	v_add_f32_e32 v166, v218, v166
	v_add_f32_e32 v166, v221, v166
	v_add_f32_e32 v166, v222, v166
	v_add_f32_e32 v166, v223, v166
	s_waitcnt lgkmcnt(0)
; #define SBAR() __builtin_amdgcn_sched_barrier(0)
; #define QKT(P0, P1, KS) do { if (MODE == 1) qkt_lds(P0, P1, KS, qs, r32, hi); else qkt(P0, P1, KS, qr, r32, hi); } while (0)
; #define SWRITE(b, i) do { *(bf16x8*)((char*)V_lds + (b) * SHM_V + vst0) = sr_[i].vs0;          \
;     *(bf16x8*)((char*)V_lds + (b) * SHM_V + vst1) = sr_[i].vs1; int kc = sc * 2;               \
;     *(bf16x8*)((char*)K_lds + (b) * SHM_K + KSWZ(sr, kc)) = sr_[i].ks0;                       \
;     *(bf16x8*)((char*)K_lds + (b) * SHM_K + KSWZ(32 + sr, kc)) = sr_[i].ks1; } while (0)
; #define SWAIT() do { if (SD == 2) asm volatile("s_waitcnt vmcnt(4)" ::: "memory"); else asm volatile("s_waitcnt vmcnt(0)" ::: "memory"); } while (0)
; template <int D0> __device__ __forceinline__ void pv_one(f32x16& od, int vb, bf16x8 pa0, bf16x8 pa1, bf16x8 pa2, bf16x8 pa3) {
;   const s16x4 l0 = tr_read<v_rd_off(D0, 0, 0)>(vb), h0 = tr_read<v_rd_off(D0, 0, 1)>(vb), l1 = tr_read<v_rd_off(D0, 1, 0)>(vb), h1 = tr_read<v_rd_off(D0, 1, 1)>(vb);
;   const s16x4 l2 = tr_read<v_rd_off(D0, 2, 0)>(vb), h2 = tr_read<v_rd_off(D0, 2, 1)>(vb), l3 = tr_read<v_rd_off(D0, 3, 0)>(vb), h3 = tr_read<v_rd_off(D0, 3, 1)>(vb);
;   asm volatile("s_waitcnt lgkmcnt(0)" ::: "memory"); SBAR();
;     ...
;   od = __builtin_amdgcn_mfma_f32_32x32x16_bf16(pa0, PK(l0, h0), od, 0, 0, 0);
;   od = __builtin_amdgcn_mfma_f32_32x32x16_bf16(pa1, PK(l1, h1), od, 0, 0, 0);
;   od = __builtin_amdgcn_mfma_f32_32x32x16_bf16(pa2, PK(l2, h2), od, 0, 0, 0);
;   od = __builtin_amdgcn_mfma_f32_32x32x16_bf16(pa3, PK(l3, h3), od, 0, 0, 0);
;     ...
; }
; __device__ __forceinline__ void pv_d0(f32x16* o, int vb, bf16x8 pa0, bf16x8 pa1, bf16x8 pa2, bf16x8 pa3) {
;   pv_one<0>(o[0], vb, pa0, pa1, pa2, pa3); pv_one<1>(o[1], vb, pa0, pa1, pa2, pa3); pv_one<2>(o[2], vb, pa0, pa1, pa2, pa3); pv_one<3>(o[3], vb, pa0, pa1, pa2, pa3);
; template <int MODE> ...
;     ...
;       SBAR(); QKT(pA0, pA1, (u16*)((char*)K_lds + s1_ * SHM_K));
;       finishSM(pB0, pB1, alB, l_reg, pa0, pa1, pa2, pa3); SBAR();
;       { const int tn = (j + 3 < NT) ? j + 3 : NT - 1; SLOAD(SE, tn); } SBAR();
;       pv_d0(o, vb0 + s0_ * (int)SHM_V, pa0, pa1, pa2, pa3); partialSM(pA0, pA1, m_reg, mnA, alA);
;       SWAIT(); SWRITE(s2_, SO);
	v_mfma_f32_32x32x16_bf16 v[68:83], v[240:243], v[128:131], v[68:83]
	v_add_u32_e32 v254, s93, v197
	ds_read_b64_tr_b16 v[230:231], v254 offset:0
	ds_read_b64_tr_b16 v[232:233], v254 offset:2048
	ds_read_b64_tr_b16 v[234:235], v254 offset:4096
	ds_read_b64_tr_b16 v[236:237], v254 offset:6144
	ds_read_b64_tr_b16 v[238:239], v254 offset:8192
	ds_read_b64_tr_b16 v[240:241], v254 offset:10240
	ds_read_b64_tr_b16 v[242:243], v254 offset:12288
	ds_read_b64_tr_b16 v[244:245], v254 offset:14336
	ds_read_b64_tr_b16 v[246:247], v254 offset:512
	ds_read_b64_tr_b16 v[248:249], v254 offset:2560
	v_exp_f32_e32 v132, v141
	v_add_f32_e32 v166, v224, v166
	v_exp_f32_e32 v133, v142
	v_add_f32_e32 v166, v225, v166
	v_exp_f32_e32 v134, v143
	v_add_f32_e32 v166, v226, v166
	v_exp_f32_e32 v135, v144
	v_add_f32_e32 v166, v227, v166
	v_exp_f32_e32 v136, v145
	v_add_f32_e32 v166, v132, v166
	v_exp_f32_e32 v137, v146
	v_add_f32_e32 v166, v133, v166
	v_exp_f32_e32 v138, v147
	v_add_f32_e32 v166, v134, v166
	v_add_f32_e32 v166, v135, v166
	v_exp_f32_e32 v141, v203
	v_add_f32_e32 v166, v136, v166
	v_exp_f32_e32 v142, v204
	v_add_f32_e32 v166, v137, v166
	v_exp_f32_e32 v143, v205
	v_add_f32_e32 v166, v138, v166
	v_exp_f32_e32 v144, v206
	v_add_f32_e32 v166, v139, v166
	v_exp_f32_e32 v145, v207
	v_add_f32_e32 v166, v141, v166
	v_exp_f32_e32 v146, v208
	v_add_f32_e32 v166, v142, v166
	v_exp_f32_e32 v147, v209
	v_add_f32_e32 v166, v143, v166
	v_add_f32_e32 v166, v144, v166
	v_add_f32_e32 v166, v145, v166
	v_add_f32_e32 v166, v146, v166
	v_add_f32_e32 v166, v147, v166
	v_add_f32_e32 v219, v140, v166
	v_mov_b32_e32 v220, v219
	s_nop 1
	v_permlane32_swap_b32_e32 v219, v220
	v_cvt_pk_bf16_f32 v204, v210, v211
	v_cvt_pk_bf16_f32 v205, v212, v213
	v_cvt_pk_bf16_f32 v206, v214, v215
	v_cvt_pk_bf16_f32 v207, v216, v217
	v_cvt_pk_bf16_f32 v208, v218, v221
	v_cvt_pk_bf16_f32 v209, v222, v223
	v_cvt_pk_bf16_f32 v210, v224, v225
	v_cvt_pk_bf16_f32 v211, v226, v227
	v_cvt_pk_bf16_f32 v212, v132, v133
	v_cvt_pk_bf16_f32 v213, v134, v135
	v_cvt_pk_bf16_f32 v214, v136, v137
	v_cvt_pk_bf16_f32 v215, v138, v139
	v_cvt_pk_bf16_f32 v222, v141, v142
	v_cvt_pk_bf16_f32 v223, v143, v144
	v_cvt_pk_bf16_f32 v224, v145, v146
	v_cvt_pk_bf16_f32 v225, v147, v140
	s_nop 0
	v_permlane32_swap_b32_e32 v204, v206
	v_permlane32_swap_b32_e32 v205, v207
	v_permlane32_swap_b32_e32 v208, v210
	v_permlane32_swap_b32_e32 v209, v211
	v_permlane32_swap_b32_e32 v212, v214
	v_permlane32_swap_b32_e32 v213, v215
	v_permlane32_swap_b32_e32 v222, v224
	v_permlane32_swap_b32_e32 v223, v225
	s_min_u32 s6, s16, s90
	s_add_i32 s6, s6, s88
	s_lshl_b32 s6, s6, 6
	v_add_u32_e32 v132, s6, v167
	v_add_u32_e32 v134, s6, v185
	v_ashrrev_i32_e32 v133, 31, v132
	v_ashrrev_i32_e32 v135, 31, v134
	v_lshlrev_b64 v[140:141], 8, v[132:133]
	v_lshlrev_b64 v[142:143], 8, v[134:135]
	v_or_b32_e32 v140, v140, v182
	v_or_b32_e32 v142, v142, v182
	v_lshl_add_u64 v[132:133], s[58:59], 0, v[140:141]
	v_lshl_add_u64 v[134:135], s[58:59], 0, v[142:143]
	v_lshl_add_u64 v[140:141], s[64:65], 0, v[140:141]
	v_lshl_add_u64 v[142:143], s[64:65], 0, v[142:143]
	global_load_dwordx4 v[136:139], v[132:133], off
	s_nop 0
	global_load_dwordx4 v[132:135], v[134:135], off
	s_nop 0
	global_load_dwordx4 v[144:147], v[140:141], off
	s_nop 0
	global_load_dwordx4 v[140:143], v[142:143], off
	s_waitcnt lgkmcnt(8)
	v_mfma_f32_32x32x16_bf16 v[52:67], v[204:207], v[230:233], v[52:67]
	ds_read_b64_tr_b16 v[250:251], v254 offset:4608
	ds_read_b64_tr_b16 v[252:253], v254 offset:6656
	s_waitcnt lgkmcnt(8)
	v_mfma_f32_32x32x16_bf16 v[52:67], v[208:211], v[234:237], v[52:67]
	ds_read_b64_tr_b16 v[230:231], v254 offset:8704
	ds_read_b64_tr_b16 v[232:233], v254 offset:10752
	s_waitcnt lgkmcnt(8)
	v_mfma_f32_32x32x16_bf16 v[52:67], v[212:215], v[238:241], v[52:67]
	ds_read_b64_tr_b16 v[234:235], v254 offset:12800
	ds_read_b64_tr_b16 v[236:237], v254 offset:14848
	s_waitcnt lgkmcnt(8)
	v_mfma_f32_32x32x16_bf16 v[52:67], v[222:225], v[242:245], v[52:67]
	ds_read_b64_tr_b16 v[238:239], v254 offset:1024
	ds_read_b64_tr_b16 v[240:241], v254 offset:3072
	s_waitcnt lgkmcnt(8)
	v_mfma_f32_32x32x16_bf16 v[36:51], v[204:207], v[246:249], v[36:51]
	ds_read_b64_tr_b16 v[242:243], v254 offset:5120
	ds_read_b64_tr_b16 v[244:245], v254 offset:7168
	s_waitcnt lgkmcnt(8)
	v_mfma_f32_32x32x16_bf16 v[36:51], v[208:211], v[250:253], v[36:51]
	ds_read_b64_tr_b16 v[246:247], v254 offset:9216
	ds_read_b64_tr_b16 v[248:249], v254 offset:11264
	s_waitcnt lgkmcnt(8)
	v_mfma_f32_32x32x16_bf16 v[36:51], v[212:215], v[230:233], v[36:51]
	ds_read_b64_tr_b16 v[250:251], v254 offset:13312
	ds_read_b64_tr_b16 v[252:253], v254 offset:15360
	s_waitcnt lgkmcnt(8)
	v_mfma_f32_32x32x16_bf16 v[36:51], v[222:225], v[234:237], v[36:51]
	ds_read_b64_tr_b16 v[230:231], v254 offset:1536
	ds_read_b64_tr_b16 v[232:233], v254 offset:3584
	s_waitcnt lgkmcnt(8)
	v_mfma_f32_32x32x16_bf16 v[20:35], v[204:207], v[238:241], v[20:35]
	ds_read_b64_tr_b16 v[234:235], v254 offset:5632
	ds_read_b64_tr_b16 v[236:237], v254 offset:7680
	s_waitcnt lgkmcnt(8)
	v_mfma_f32_32x32x16_bf16 v[20:35], v[208:211], v[242:245], v[20:35]
	ds_read_b64_tr_b16 v[238:239], v254 offset:9728
	ds_read_b64_tr_b16 v[240:241], v254 offset:11776
	s_waitcnt lgkmcnt(8)
	v_mfma_f32_32x32x16_bf16 v[20:35], v[212:215], v[246:249], v[20:35]
	ds_read_b64_tr_b16 v[242:243], v254 offset:13824
	ds_read_b64_tr_b16 v[244:245], v254 offset:15872
	s_waitcnt lgkmcnt(8)
	v_mfma_f32_32x32x16_bf16 v[20:35], v[222:225], v[250:253], v[20:35]
	s_waitcnt lgkmcnt(6)
	v_mfma_f32_32x32x16_bf16 v[4:19], v[204:207], v[230:233], v[4:19]
	s_waitcnt lgkmcnt(4)
	v_mfma_f32_32x32x16_bf16 v[4:19], v[208:211], v[234:237], v[4:19]
	s_waitcnt lgkmcnt(2)
	v_mfma_f32_32x32x16_bf16 v[4:19], v[212:215], v[238:241], v[4:19]
	s_waitcnt lgkmcnt(0)
	v_mfma_f32_32x32x16_bf16 v[4:19], v[222:225], v[242:245], v[4:19]
	s_add_i32 s30, s94, 0
	v_add_u32_e32 v203, s30, v184
	s_waitcnt vmcnt(4)
	s_waitcnt vmcnt(7)
	ds_write_b128 v203, v[152:155]
	v_add_u32_e32 v152, s30, v186
	s_waitcnt vmcnt(6)
	ds_write_b128 v152, v[148:151]
	v_add_u32_e32 v148, s30, v187
	s_waitcnt vmcnt(5)
	ds_write_b128 v148, v[160:163] offset:49152
	v_add_u32_e32 v148, s30, v188
	s_waitcnt vmcnt(4)
	ds_write_b128 v148, v[156:159] offset:49152
	s_waitcnt lgkmcnt(0)
	s_barrier
; __device__ __forceinline__ void partialSM(f32x16& p0, f32x16& p1, float& m_reg, float& mn, float& alpha) {
;   constexpr float C = SCALE * 1.4426950408889634f;
;   float pmax = p0[0]; for (int r = 1; r < 16; ++r) pmax = fmaxf(pmax, p0[r]); for (int r = 0; r < 16; ++r) pmax = fmaxf(pmax, p1[r]);
;   { auto rr = __builtin_amdgcn_permlane32_swap(__float_as_uint(pmax), __float_as_uint(pmax), false, false);
;     pmax = fmaxf(__uint_as_float(rr[0]), __uint_as_float(rr[1])); }
;   if (__builtin_expect(__all(pmax - m_reg <= THR / SCALE), 1)) { mn = m_reg; alpha = 1.f; }
;   else { mn = fmaxf(m_reg, pmax); alpha = __builtin_amdgcn_exp2f((m_reg - mn) * C); m_reg = mn; }
	v_max_f32_e32 v166, v85, v85
	v_max_f32_e32 v203, v84, v84
	v_max_f32_e32 v166, v203, v166
	v_max3_f32 v166, v166, v86, v87
	v_max3_f32 v166, v166, v88, v89
	v_max3_f32 v166, v166, v90, v91
	v_max3_f32 v166, v166, v92, v93
	v_max3_f32 v166, v166, v94, v95
	v_max3_f32 v166, v166, v96, v97
	v_max3_f32 v166, v166, v98, v99
	v_max3_f32 v166, v166, v68, v69
	v_max3_f32 v166, v166, v70, v71
	v_max3_f32 v166, v166, v72, v73
	v_max3_f32 v166, v166, v74, v75
	v_max3_f32 v166, v166, v76, v77
	v_max3_f32 v166, v166, v78, v79
	v_max3_f32 v166, v166, v80, v81
	v_max3_f32 v166, v166, v82, v83
	v_mov_b32_e32 v203, v166
	s_nop 1
	v_permlane32_swap_b32_e32 v166, v203
	v_max_f32_e32 v203, v203, v203
	v_max_f32_e32 v166, v166, v166
	v_max_f32_e32 v166, v166, v203
	v_sub_f32_e32 v203, v166, v2
	v_cmp_ge_f32_e32 vcc, s74, v203
	v_max_f32_e32 v203, v2, v2
	v_max_f32_e32 v166, v203, v166
	v_sub_f32_e32 v203, v2, v166
	v_mul_f32_e32 v203, 0x3e0293ee, v203
	v_exp_f32_e32 v203, v203
	s_cmp_eq_u64 vcc, exec
	s_cselect_b64 s[6:7], -1, 0
	v_cndmask_b32_e64 v221, v203, 1.0, s[6:7]
	v_cmp_gt_f32_e32 vcc, 1.0, v221
	s_cbranch_vccz .Lstg_r2
	s_and_saveexec_b64 s[66:67], s[4:5]
	ds_write_b32 v183, v221 offset:128
	s_or_b64 exec, exec, s[66:67]
	s_waitcnt lgkmcnt(0)
	v_add_u32_e32 v160, v181, v180
	ds_read_b128 v[148:151], v160 offset:224
	ds_read_b128 v[152:155], v160 offset:192
	ds_read_b128 v[156:159], v160 offset:160
	ds_read_b128 v[160:163], v160 offset:128
	s_waitcnt lgkmcnt(3)
	v_pk_mul_f32 v[64:65], v[64:65], v[148:149]
	s_waitcnt lgkmcnt(2)
	v_pk_mul_f32 v[60:61], v[60:61], v[152:153]
	s_waitcnt lgkmcnt(1)
	v_pk_mul_f32 v[56:57], v[56:57], v[156:157]
	v_pk_mul_f32 v[66:67], v[66:67], v[150:151]
	v_pk_mul_f32 v[62:63], v[62:63], v[154:155]
	v_pk_mul_f32 v[58:59], v[58:59], v[158:159]
	s_waitcnt lgkmcnt(0)
	v_pk_mul_f32 v[54:55], v[54:55], v[162:163]
	v_pk_mul_f32 v[52:53], v[52:53], v[160:161]
	v_pk_mul_f32 v[48:49], v[48:49], v[148:149]
	v_pk_mul_f32 v[44:45], v[44:45], v[152:153]
	v_pk_mul_f32 v[40:41], v[40:41], v[156:157]
	v_pk_mul_f32 v[50:51], v[50:51], v[150:151]
	v_pk_mul_f32 v[46:47], v[46:47], v[154:155]
	v_pk_mul_f32 v[42:43], v[42:43], v[158:159]
	v_pk_mul_f32 v[38:39], v[38:39], v[162:163]
	v_pk_mul_f32 v[36:37], v[36:37], v[160:161]
	v_pk_mul_f32 v[32:33], v[32:33], v[148:149]
	v_pk_mul_f32 v[28:29], v[28:29], v[152:153]
	v_pk_mul_f32 v[24:25], v[24:25], v[156:157]
	v_pk_mul_f32 v[34:35], v[34:35], v[150:151]
	v_pk_mul_f32 v[30:31], v[30:31], v[154:155]
	v_pk_mul_f32 v[26:27], v[26:27], v[158:159]
	v_pk_mul_f32 v[22:23], v[22:23], v[162:163]
	v_pk_mul_f32 v[20:21], v[20:21], v[160:161]
	v_pk_mul_f32 v[16:17], v[16:17], v[148:149]
	v_pk_mul_f32 v[12:13], v[12:13], v[152:153]
	v_pk_mul_f32 v[8:9], v[8:9], v[156:157]
	v_pk_mul_f32 v[18:19], v[18:19], v[150:151]
	v_pk_mul_f32 v[14:15], v[14:15], v[154:155]
	v_pk_mul_f32 v[10:11], v[10:11], v[158:159]
	v_pk_mul_f32 v[6:7], v[6:7], v[162:163]
	v_pk_mul_f32 v[4:5], v[4:5], v[160:161]
